# merged the vmcnt and lgkmcnt waits of each GEMM load segment into one s_waitcnt
# speedup vs baseline: 1.0053x; 1.0053x over previous
.LBB0_67:
	s_add_u32 s34, s6, 0xfff80080
	s_addc_u32 s35, s7, -1
	s_add_i32 s53, 0, 0x10000
	s_cmp_eq_u32 s52, 28
	s_cselect_b32 s37, s25, s35
	s_cselect_b32 s36, s29, s34
	s_cselect_b32 s35, s23, s51
	s_cselect_b32 s34, s49, s50
	s_add_i32 s56, 0, 0x14000
	v_add_u32_e32 v142, s53, v187
	v_add_u32_e32 v158, s56, v187
	ds_read_b128 v[130:133], v142
	ds_read_b128 v[134:137], v142 offset:1024
	ds_read_b128 v[138:141], v142 offset:2048
	ds_read_b128 v[142:145], v142 offset:3072
	ds_read_b128 v[146:149], v158
	ds_read_b128 v[150:153], v158 offset:1024
	ds_read_b128 v[154:157], v158 offset:2048
	ds_read_b128 v[158:161], v158 offset:3072
	v_lshl_add_u64 v[184:185], s[6:7], 0, v[168:169]
	s_add_i32 m0, s43, 0xc000
	ds_read_b128 v[172:175], v199
	ds_read_b128 v[178:181], v199 offset:1024
	ds_read_b128 v[188:191], v199 offset:2048
	ds_read_b128 v[200:203], v199 offset:3072
	ds_read_b128 v[204:207], v199 offset:4096
	ds_read_b128 v[216:219], v199 offset:5120
	ds_read_b128 v[220:223], v199 offset:6144
	ds_read_b128 v[224:227], v199 offset:7168
	global_load_lds_dwordx4 v[184:185], off
	v_lshl_add_u64 v[184:185], s[6:7], 0, v[170:171]
	s_add_i32 m0, s43, 0xe000
	s_nop 0
	global_load_lds_dwordx4 v[184:185], off
	s_waitcnt vmcnt(8) lgkmcnt(0)
	s_barrier
	s_setprio 1
	v_mfma_f32_16x16x32_bf16 v[126:129], v[130:133], v[172:175], v[126:129]
	v_mfma_f32_16x16x32_bf16 v[122:125], v[138:141], v[172:175], v[122:125]
	v_mfma_f32_16x16x32_bf16 v[110:113], v[130:133], v[188:191], v[110:113]
	v_mfma_f32_16x16x32_bf16 v[106:109], v[138:141], v[188:191], v[106:109]
	v_mfma_f32_16x16x32_bf16 v[98:101], v[130:133], v[204:207], v[98:101]
	v_mfma_f32_16x16x32_bf16 v[90:93], v[138:141], v[204:207], v[90:93]
	v_mfma_f32_16x16x32_bf16 v[82:85], v[130:133], v[220:223], v[82:85]
	v_mfma_f32_16x16x32_bf16 v[74:77], v[138:141], v[220:223], v[74:77]
	v_mfma_f32_16x16x32_bf16 v[126:129], v[134:137], v[178:181], v[126:129]
	v_mfma_f32_16x16x32_bf16 v[122:125], v[142:145], v[178:181], v[122:125]
	v_mfma_f32_16x16x32_bf16 v[110:113], v[134:137], v[200:203], v[110:113]
	v_mfma_f32_16x16x32_bf16 v[106:109], v[142:145], v[200:203], v[106:109]
	v_mfma_f32_16x16x32_bf16 v[98:101], v[134:137], v[216:219], v[98:101]
	v_mfma_f32_16x16x32_bf16 v[90:93], v[142:145], v[216:219], v[90:93]
	v_mfma_f32_16x16x32_bf16 v[82:85], v[134:137], v[224:227], v[82:85]
	v_mfma_f32_16x16x32_bf16 v[74:77], v[142:145], v[224:227], v[74:77]
	v_mfma_f32_16x16x32_bf16 v[118:121], v[146:149], v[172:175], v[118:121]
	v_mfma_f32_16x16x32_bf16 v[114:117], v[154:157], v[172:175], v[114:117]
	v_mfma_f32_16x16x32_bf16 v[102:105], v[146:149], v[188:191], v[102:105]
	v_mfma_f32_16x16x32_bf16 v[94:97], v[154:157], v[188:191], v[94:97]
	v_mfma_f32_16x16x32_bf16 v[86:89], v[146:149], v[204:207], v[86:89]
	v_mfma_f32_16x16x32_bf16 v[78:81], v[154:157], v[204:207], v[78:81]
	v_mfma_f32_16x16x32_bf16 v[70:73], v[146:149], v[220:223], v[70:73]
	v_mfma_f32_16x16x32_bf16 v[66:69], v[154:157], v[220:223], v[66:69]
	v_mfma_f32_16x16x32_bf16 v[118:121], v[150:153], v[178:181], v[118:121]
	v_mfma_f32_16x16x32_bf16 v[114:117], v[158:161], v[178:181], v[114:117]
	v_mfma_f32_16x16x32_bf16 v[102:105], v[150:153], v[200:203], v[102:105]
	v_mfma_f32_16x16x32_bf16 v[94:97], v[158:161], v[200:203], v[94:97]
	v_mfma_f32_16x16x32_bf16 v[86:89], v[150:153], v[216:219], v[86:89]
	v_mfma_f32_16x16x32_bf16 v[78:81], v[158:161], v[216:219], v[78:81]
	v_mfma_f32_16x16x32_bf16 v[70:73], v[150:153], v[224:227], v[70:73]
	v_mfma_f32_16x16x32_bf16 v[66:69], v[158:161], v[224:227], v[66:69]
	s_setprio 0
	s_barrier
	s_add_i32 s53, s53, s42
	v_lshl_add_u64 v[184:185], s[34:35], 0, v[210:211]
	s_mov_b32 m0, s53
	ds_read_b128 v[172:175], v199 offset:16384
	ds_read_b128 v[178:181], v199 offset:17408
	ds_read_b128 v[188:191], v199 offset:18432
	ds_read_b128 v[200:203], v199 offset:19456
	ds_read_b128 v[204:207], v199 offset:20480
	ds_read_b128 v[216:219], v199 offset:21504
	ds_read_b128 v[220:223], v199 offset:22528
	ds_read_b128 v[224:227], v199 offset:23552
	global_load_lds_dwordx4 v[184:185], off
	s_add_i32 m0, s53, 0x2000
	s_add_u32 s54, s34, 0x80000
	v_lshl_add_u64 v[192:193], s[34:35], 0, v[162:163]
	s_addc_u32 s55, s35, 0
	s_add_i32 s53, s56, s42
	global_load_lds_dwordx4 v[192:193], off
	v_lshl_add_u64 v[196:197], s[54:55], 0, v[210:211]
	s_mov_b32 m0, s53
	v_lshl_add_u64 v[208:209], s[36:37], 0, v[164:165]
	global_load_lds_dwordx4 v[196:197], off
	v_lshl_add_u64 v[196:197], s[54:55], 0, v[162:163]
	s_add_i32 m0, s53, 0x2000
	s_nop 0
	global_load_lds_dwordx4 v[196:197], off
	v_lshl_add_u64 v[196:197], s[36:37], 0, v[166:167]
	s_mov_b32 m0, s43
	s_nop 0
	global_load_lds_dwordx4 v[196:197], off
	s_mov_b32 m0, s44
	s_nop 0
	global_load_lds_dwordx4 v[208:209], off
	s_waitcnt vmcnt(8) lgkmcnt(0)
	s_barrier
	s_setprio 1
	v_mfma_f32_16x16x32_bf16 v[62:65], v[130:133], v[172:175], v[62:65]
	v_mfma_f32_16x16x32_bf16 v[58:61], v[138:141], v[172:175], v[58:61]
	v_mfma_f32_16x16x32_bf16 v[50:53], v[130:133], v[188:191], v[50:53]
	v_mfma_f32_16x16x32_bf16 v[42:45], v[138:141], v[188:191], v[42:45]
	v_mfma_f32_16x16x32_bf16 v[34:37], v[130:133], v[204:207], v[34:37]
	v_mfma_f32_16x16x32_bf16 v[26:29], v[138:141], v[204:207], v[26:29]
	v_mfma_f32_16x16x32_bf16 v[14:17], v[130:133], v[220:223], v[14:17]
	v_mfma_f32_16x16x32_bf16 v[10:13], v[138:141], v[220:223], v[10:13]
	v_mfma_f32_16x16x32_bf16 v[62:65], v[134:137], v[178:181], v[62:65]
	v_mfma_f32_16x16x32_bf16 v[58:61], v[142:145], v[178:181], v[58:61]
	v_mfma_f32_16x16x32_bf16 v[50:53], v[134:137], v[200:203], v[50:53]
	v_mfma_f32_16x16x32_bf16 v[42:45], v[142:145], v[200:203], v[42:45]
	v_mfma_f32_16x16x32_bf16 v[34:37], v[134:137], v[216:219], v[34:37]
	v_mfma_f32_16x16x32_bf16 v[26:29], v[142:145], v[216:219], v[26:29]
	v_mfma_f32_16x16x32_bf16 v[14:17], v[134:137], v[224:227], v[14:17]
	v_mfma_f32_16x16x32_bf16 v[10:13], v[142:145], v[224:227], v[10:13]
	v_mfma_f32_16x16x32_bf16 v[54:57], v[146:149], v[172:175], v[54:57]
	v_mfma_f32_16x16x32_bf16 v[46:49], v[154:157], v[172:175], v[46:49]
	v_mfma_f32_16x16x32_bf16 v[38:41], v[146:149], v[188:191], v[38:41]
	v_mfma_f32_16x16x32_bf16 v[30:33], v[154:157], v[188:191], v[30:33]
	v_mfma_f32_16x16x32_bf16 v[22:25], v[146:149], v[204:207], v[22:25]
	v_mfma_f32_16x16x32_bf16 v[18:21], v[154:157], v[204:207], v[18:21]
	v_mfma_f32_16x16x32_bf16 v[6:9], v[146:149], v[220:223], v[6:9]
	v_mfma_f32_16x16x32_bf16 v[2:5], v[154:157], v[220:223], v[2:5]
	v_mfma_f32_16x16x32_bf16 v[54:57], v[150:153], v[178:181], v[54:57]
	v_mfma_f32_16x16x32_bf16 v[46:49], v[158:161], v[178:181], v[46:49]
	v_mfma_f32_16x16x32_bf16 v[38:41], v[150:153], v[200:203], v[38:41]
	v_mfma_f32_16x16x32_bf16 v[30:33], v[158:161], v[200:203], v[30:33]
	v_mfma_f32_16x16x32_bf16 v[22:25], v[150:153], v[216:219], v[22:25]
	v_mfma_f32_16x16x32_bf16 v[18:21], v[158:161], v[216:219], v[18:21]
	v_mfma_f32_16x16x32_bf16 v[6:9], v[150:153], v[224:227], v[6:9]
	v_mfma_f32_16x16x32_bf16 v[2:5], v[158:161], v[224:227], v[2:5]
	s_setprio 0
	s_barrier
	s_add_i32 s53, 0, 0x18000
	s_add_i32 s54, 0, 0x1c000
	v_add_u32_e32 v142, s53, v187
	v_add_u32_e32 v158, s54, v187
	ds_read_b128 v[130:133], v142
	ds_read_b128 v[134:137], v142 offset:1024
	ds_read_b128 v[138:141], v142 offset:2048
	ds_read_b128 v[142:145], v142 offset:3072
	ds_read_b128 v[146:149], v158
	ds_read_b128 v[150:153], v158 offset:1024
	ds_read_b128 v[154:157], v158 offset:2048
	ds_read_b128 v[158:161], v158 offset:3072
	s_add_u32 s36, s36, 0x80000
	s_addc_u32 s37, s37, 0
	s_mov_b32 m0, s45
	v_lshl_add_u64 v[212:213], s[36:37], 0, v[166:167]
	ds_read_b128 v[172:175], v199 offset:32768
	ds_read_b128 v[178:181], v199 offset:33792
	ds_read_b128 v[188:191], v199 offset:34816
	ds_read_b128 v[200:203], v199 offset:35840
	ds_read_b128 v[204:207], v199 offset:36864
	ds_read_b128 v[216:219], v199 offset:37888
	ds_read_b128 v[220:223], v199 offset:38912
	ds_read_b128 v[224:227], v199 offset:39936
	global_load_lds_dwordx4 v[212:213], off
	v_lshl_add_u64 v[212:213], s[36:37], 0, v[164:165]
	s_mov_b32 m0, s46
	s_nop 0
	global_load_lds_dwordx4 v[212:213], off
	s_waitcnt vmcnt(8) lgkmcnt(0)
	s_barrier
	s_setprio 1
	v_mfma_f32_16x16x32_bf16 v[126:129], v[130:133], v[172:175], v[126:129]
	v_mfma_f32_16x16x32_bf16 v[122:125], v[138:141], v[172:175], v[122:125]
	v_mfma_f32_16x16x32_bf16 v[110:113], v[130:133], v[188:191], v[110:113]
	v_mfma_f32_16x16x32_bf16 v[106:109], v[138:141], v[188:191], v[106:109]
	v_mfma_f32_16x16x32_bf16 v[98:101], v[130:133], v[204:207], v[98:101]
	v_mfma_f32_16x16x32_bf16 v[90:93], v[138:141], v[204:207], v[90:93]
	v_mfma_f32_16x16x32_bf16 v[82:85], v[130:133], v[220:223], v[82:85]
	v_mfma_f32_16x16x32_bf16 v[74:77], v[138:141], v[220:223], v[74:77]
	v_mfma_f32_16x16x32_bf16 v[126:129], v[134:137], v[178:181], v[126:129]
	v_mfma_f32_16x16x32_bf16 v[122:125], v[142:145], v[178:181], v[122:125]
	v_mfma_f32_16x16x32_bf16 v[110:113], v[134:137], v[200:203], v[110:113]
	v_mfma_f32_16x16x32_bf16 v[106:109], v[142:145], v[200:203], v[106:109]
	v_mfma_f32_16x16x32_bf16 v[98:101], v[134:137], v[216:219], v[98:101]
	v_mfma_f32_16x16x32_bf16 v[90:93], v[142:145], v[216:219], v[90:93]
	v_mfma_f32_16x16x32_bf16 v[82:85], v[134:137], v[224:227], v[82:85]
	v_mfma_f32_16x16x32_bf16 v[74:77], v[142:145], v[224:227], v[74:77]
	v_mfma_f32_16x16x32_bf16 v[118:121], v[146:149], v[172:175], v[118:121]
	v_mfma_f32_16x16x32_bf16 v[114:117], v[154:157], v[172:175], v[114:117]
	v_mfma_f32_16x16x32_bf16 v[102:105], v[146:149], v[188:191], v[102:105]
	v_mfma_f32_16x16x32_bf16 v[94:97], v[154:157], v[188:191], v[94:97]
	v_mfma_f32_16x16x32_bf16 v[86:89], v[146:149], v[204:207], v[86:89]
	v_mfma_f32_16x16x32_bf16 v[78:81], v[154:157], v[204:207], v[78:81]
	v_mfma_f32_16x16x32_bf16 v[70:73], v[146:149], v[220:223], v[70:73]
	v_mfma_f32_16x16x32_bf16 v[66:69], v[154:157], v[220:223], v[66:69]
	v_mfma_f32_16x16x32_bf16 v[118:121], v[150:153], v[178:181], v[118:121]
	v_mfma_f32_16x16x32_bf16 v[114:117], v[158:161], v[178:181], v[114:117]
	v_mfma_f32_16x16x32_bf16 v[102:105], v[150:153], v[200:203], v[102:105]
	v_mfma_f32_16x16x32_bf16 v[94:97], v[158:161], v[200:203], v[94:97]
	v_mfma_f32_16x16x32_bf16 v[86:89], v[150:153], v[216:219], v[86:89]
	v_mfma_f32_16x16x32_bf16 v[78:81], v[158:161], v[216:219], v[78:81]
	v_mfma_f32_16x16x32_bf16 v[70:73], v[150:153], v[224:227], v[70:73]
	v_mfma_f32_16x16x32_bf16 v[66:69], v[158:161], v[224:227], v[66:69]
	s_setprio 0
	s_barrier
	s_add_i32 s36, s53, s42
	v_lshl_add_u64 v[184:185], v[184:185], 0, s[64:65]
	s_mov_b32 m0, s36
	ds_read_b128 v[172:175], v199 offset:49152
	ds_read_b128 v[178:181], v199 offset:50176
	ds_read_b128 v[188:191], v199 offset:51200
	ds_read_b128 v[200:203], v199 offset:52224
	ds_read_b128 v[204:207], v199 offset:53248
	ds_read_b128 v[216:219], v199 offset:54272
	ds_read_b128 v[220:223], v199 offset:55296
	ds_read_b128 v[224:227], v199 offset:56320
	global_load_lds_dwordx4 v[184:185], off
	s_add_i32 m0, s36, 0x2000
	s_add_u32 s34, s34, 0x80080
	v_lshl_add_u64 v[184:185], v[192:193], 0, s[64:65]
	s_addc_u32 s35, s35, 0
	s_add_i32 s36, s54, s42
	global_load_lds_dwordx4 v[184:185], off
	v_lshl_add_u64 v[184:185], s[34:35], 0, v[210:211]
	s_mov_b32 m0, s36
	s_nop 0
	global_load_lds_dwordx4 v[184:185], off
	v_lshl_add_u64 v[184:185], s[34:35], 0, v[162:163]
	s_add_i32 m0, s36, 0x2000
	s_nop 0
	global_load_lds_dwordx4 v[184:185], off
	v_lshl_add_u64 v[184:185], v[196:197], 0, s[64:65]
	s_mov_b32 m0, s47
	s_nop 0
	global_load_lds_dwordx4 v[184:185], off
	v_lshl_add_u64 v[184:185], v[208:209], 0, s[64:65]
	s_mov_b32 m0, s48
	s_nop 0
	global_load_lds_dwordx4 v[184:185], off
	s_waitcnt vmcnt(8) lgkmcnt(0)
	s_barrier
	s_setprio 1
	v_mfma_f32_16x16x32_bf16 v[62:65], v[130:133], v[172:175], v[62:65]
	v_mfma_f32_16x16x32_bf16 v[58:61], v[138:141], v[172:175], v[58:61]
	v_mfma_f32_16x16x32_bf16 v[50:53], v[130:133], v[188:191], v[50:53]
	v_mfma_f32_16x16x32_bf16 v[42:45], v[138:141], v[188:191], v[42:45]
	v_mfma_f32_16x16x32_bf16 v[34:37], v[130:133], v[204:207], v[34:37]
	v_mfma_f32_16x16x32_bf16 v[26:29], v[138:141], v[204:207], v[26:29]
	v_mfma_f32_16x16x32_bf16 v[14:17], v[130:133], v[220:223], v[14:17]
	v_mfma_f32_16x16x32_bf16 v[10:13], v[138:141], v[220:223], v[10:13]
	v_mfma_f32_16x16x32_bf16 v[62:65], v[134:137], v[178:181], v[62:65]
	v_mfma_f32_16x16x32_bf16 v[58:61], v[142:145], v[178:181], v[58:61]
	v_mfma_f32_16x16x32_bf16 v[50:53], v[134:137], v[200:203], v[50:53]
	v_mfma_f32_16x16x32_bf16 v[42:45], v[142:145], v[200:203], v[42:45]
	v_mfma_f32_16x16x32_bf16 v[34:37], v[134:137], v[216:219], v[34:37]
	v_mfma_f32_16x16x32_bf16 v[26:29], v[142:145], v[216:219], v[26:29]
	v_mfma_f32_16x16x32_bf16 v[14:17], v[134:137], v[224:227], v[14:17]
	v_mfma_f32_16x16x32_bf16 v[10:13], v[142:145], v[224:227], v[10:13]
	v_mfma_f32_16x16x32_bf16 v[54:57], v[146:149], v[172:175], v[54:57]
	v_mfma_f32_16x16x32_bf16 v[46:49], v[154:157], v[172:175], v[46:49]
	v_mfma_f32_16x16x32_bf16 v[38:41], v[146:149], v[188:191], v[38:41]
	v_mfma_f32_16x16x32_bf16 v[30:33], v[154:157], v[188:191], v[30:33]
	v_mfma_f32_16x16x32_bf16 v[22:25], v[146:149], v[204:207], v[22:25]
	v_mfma_f32_16x16x32_bf16 v[18:21], v[154:157], v[204:207], v[18:21]
	v_mfma_f32_16x16x32_bf16 v[6:9], v[146:149], v[220:223], v[6:9]
	v_mfma_f32_16x16x32_bf16 v[2:5], v[154:157], v[220:223], v[2:5]
	v_mfma_f32_16x16x32_bf16 v[54:57], v[150:153], v[178:181], v[54:57]
	v_mfma_f32_16x16x32_bf16 v[46:49], v[158:161], v[178:181], v[46:49]
	v_mfma_f32_16x16x32_bf16 v[38:41], v[150:153], v[200:203], v[38:41]
	v_mfma_f32_16x16x32_bf16 v[30:33], v[158:161], v[200:203], v[30:33]
	v_mfma_f32_16x16x32_bf16 v[22:25], v[150:153], v[216:219], v[22:25]
	v_mfma_f32_16x16x32_bf16 v[18:21], v[158:161], v[216:219], v[18:21]
	v_mfma_f32_16x16x32_bf16 v[6:9], v[150:153], v[224:227], v[6:9]
	v_mfma_f32_16x16x32_bf16 v[2:5], v[158:161], v[224:227], v[2:5]
	s_setprio 0
	s_barrier
	s_add_i32 s52, s52, 2
	s_add_u32 s6, s6, 0x100
	s_addc_u32 s7, s7, 0
	s_add_u32 s50, s50, 0x100
	s_addc_u32 s51, s51, 0
	s_cmp_gt_u32 s52, 29
	s_cbranch_scc0 .LBB0_67
	s_and_b64 vcc, exec, s[18:19]
	s_cbranch_vccz .LBB0_70
	s_barrier

.LBB0_116:
	s_add_u32 s30, s6, 0xfff80080
	s_addc_u32 s31, s7, -1
	s_add_i32 s52, 0, 0x10000
	s_cmp_eq_u32 s51, 28
	s_cselect_b32 s35, s23, s31
	s_cselect_b32 s34, s28, s30
	s_cselect_b32 s31, s21, s50
	s_cselect_b32 s30, s29, s49
	s_add_i32 s54, 0, 0x14000
	v_add_u32_e32 v78, s52, v240
	v_add_u32_e32 v98, s54, v240
	ds_read_b128 v[66:69], v78
	ds_read_b128 v[70:73], v78 offset:1024
	ds_read_b128 v[74:77], v78 offset:2048
	ds_read_b128 v[78:81], v78 offset:3072
	ds_read_b128 v[82:85], v98
	ds_read_b128 v[86:89], v98 offset:1024
	ds_read_b128 v[90:93], v98 offset:2048
	ds_read_b128 v[98:101], v98 offset:3072
	v_lshl_add_u64 v[212:213], s[6:7], 0, v[182:183]
	s_add_i32 m0, s37, 0xc000
	ds_read_b128 v[186:189], v241
	ds_read_b128 v[190:193], v241 offset:1024
	ds_read_b128 v[194:197], v241 offset:2048
	ds_read_b128 v[198:201], v241 offset:3072
	ds_read_b128 v[202:205], v241 offset:4096
	ds_read_b128 v[206:209], v241 offset:5120
	ds_read_b128 v[216:219], v241 offset:6144
	ds_read_b128 v[220:223], v241 offset:7168
	global_load_lds_dwordx4 v[212:213], off
	v_lshl_add_u64 v[212:213], s[6:7], 0, v[184:185]
	s_add_i32 m0, s37, 0xe000
	s_nop 0
	global_load_lds_dwordx4 v[212:213], off
	s_waitcnt vmcnt(8) lgkmcnt(0)
	s_barrier
	s_setprio 1
	v_mfma_f32_16x16x32_bf16 v[158:161], v[66:69], v[186:189], v[158:161]
	v_mfma_f32_16x16x32_bf16 v[154:157], v[74:77], v[186:189], v[154:157]
	v_mfma_f32_16x16x32_bf16 v[142:145], v[66:69], v[194:197], v[142:145]
	v_mfma_f32_16x16x32_bf16 v[138:141], v[74:77], v[194:197], v[138:141]
	v_mfma_f32_16x16x32_bf16 v[126:129], v[66:69], v[202:205], v[126:129]
	v_mfma_f32_16x16x32_bf16 v[122:125], v[74:77], v[202:205], v[122:125]
	v_mfma_f32_16x16x32_bf16 v[110:113], v[66:69], v[216:219], v[110:113]
	v_mfma_f32_16x16x32_bf16 v[106:109], v[74:77], v[216:219], v[106:109]
	v_mfma_f32_16x16x32_bf16 v[158:161], v[70:73], v[190:193], v[158:161]
	v_mfma_f32_16x16x32_bf16 v[154:157], v[78:81], v[190:193], v[154:157]
	v_mfma_f32_16x16x32_bf16 v[142:145], v[70:73], v[198:201], v[142:145]
	v_mfma_f32_16x16x32_bf16 v[138:141], v[78:81], v[198:201], v[138:141]
	v_mfma_f32_16x16x32_bf16 v[126:129], v[70:73], v[206:209], v[126:129]
	v_mfma_f32_16x16x32_bf16 v[122:125], v[78:81], v[206:209], v[122:125]
	v_mfma_f32_16x16x32_bf16 v[110:113], v[70:73], v[220:223], v[110:113]
	v_mfma_f32_16x16x32_bf16 v[106:109], v[78:81], v[220:223], v[106:109]
	v_mfma_f32_16x16x32_bf16 v[150:153], v[82:85], v[186:189], v[150:153]
	v_mfma_f32_16x16x32_bf16 v[146:149], v[90:93], v[186:189], v[146:149]
	v_mfma_f32_16x16x32_bf16 v[134:137], v[82:85], v[194:197], v[134:137]
	v_mfma_f32_16x16x32_bf16 v[130:133], v[90:93], v[194:197], v[130:133]
	v_mfma_f32_16x16x32_bf16 v[118:121], v[82:85], v[202:205], v[118:121]
	v_mfma_f32_16x16x32_bf16 v[114:117], v[90:93], v[202:205], v[114:117]
	v_mfma_f32_16x16x32_bf16 v[102:105], v[82:85], v[216:219], v[102:105]
	v_mfma_f32_16x16x32_bf16 v[94:97], v[90:93], v[216:219], v[94:97]
	v_mfma_f32_16x16x32_bf16 v[150:153], v[86:89], v[190:193], v[150:153]
	v_mfma_f32_16x16x32_bf16 v[146:149], v[98:101], v[190:193], v[146:149]
	v_mfma_f32_16x16x32_bf16 v[134:137], v[86:89], v[198:201], v[134:137]
	v_mfma_f32_16x16x32_bf16 v[130:133], v[98:101], v[198:201], v[130:133]
	v_mfma_f32_16x16x32_bf16 v[118:121], v[86:89], v[206:209], v[118:121]
	v_mfma_f32_16x16x32_bf16 v[114:117], v[98:101], v[206:209], v[114:117]
	v_mfma_f32_16x16x32_bf16 v[102:105], v[86:89], v[220:223], v[102:105]
	v_mfma_f32_16x16x32_bf16 v[94:97], v[98:101], v[220:223], v[94:97]
	s_setprio 0
	s_barrier
	s_add_i32 s52, s52, s36
	v_lshl_add_u64 v[212:213], s[30:31], 0, v[166:167]
	s_mov_b32 m0, s52
	ds_read_b128 v[186:189], v241 offset:16384
	ds_read_b128 v[190:193], v241 offset:17408
	ds_read_b128 v[194:197], v241 offset:18432
	ds_read_b128 v[198:201], v241 offset:19456
	ds_read_b128 v[202:205], v241 offset:20480
	ds_read_b128 v[206:209], v241 offset:21504
	ds_read_b128 v[216:219], v241 offset:22528
	ds_read_b128 v[220:223], v241 offset:23552
	global_load_lds_dwordx4 v[212:213], off
	s_add_i32 m0, s52, 0x2000
	s_add_u32 s52, s30, 0x80000
	v_lshl_add_u64 v[214:215], s[30:31], 0, v[162:163]
	s_addc_u32 s53, s31, 0
	s_add_i32 s54, s54, s36
	global_load_lds_dwordx4 v[214:215], off
	v_lshl_add_u64 v[224:225], s[52:53], 0, v[166:167]
	s_mov_b32 m0, s54
	v_lshl_add_u64 v[226:227], s[34:35], 0, v[164:165]
	global_load_lds_dwordx4 v[224:225], off
	v_lshl_add_u64 v[224:225], s[52:53], 0, v[162:163]
	s_add_i32 m0, s54, 0x2000
	s_nop 0
	global_load_lds_dwordx4 v[224:225], off
	v_lshl_add_u64 v[224:225], s[34:35], 0, v[168:169]
	s_mov_b32 m0, s37
	s_nop 0
	global_load_lds_dwordx4 v[224:225], off
	s_mov_b32 m0, s42
	s_nop 0
	global_load_lds_dwordx4 v[226:227], off
	s_waitcnt vmcnt(8) lgkmcnt(0)
	s_barrier
	s_setprio 1
	v_mfma_f32_16x16x32_bf16 v[62:65], v[66:69], v[186:189], v[62:65]
	v_mfma_f32_16x16x32_bf16 v[58:61], v[74:77], v[186:189], v[58:61]
	v_mfma_f32_16x16x32_bf16 v[46:49], v[66:69], v[194:197], v[46:49]
	v_mfma_f32_16x16x32_bf16 v[42:45], v[74:77], v[194:197], v[42:45]
	v_mfma_f32_16x16x32_bf16 v[30:33], v[66:69], v[202:205], v[30:33]
	v_mfma_f32_16x16x32_bf16 v[26:29], v[74:77], v[202:205], v[26:29]
	v_mfma_f32_16x16x32_bf16 v[14:17], v[66:69], v[216:219], v[14:17]
	v_mfma_f32_16x16x32_bf16 v[10:13], v[74:77], v[216:219], v[10:13]
	v_mfma_f32_16x16x32_bf16 v[62:65], v[70:73], v[190:193], v[62:65]
	v_mfma_f32_16x16x32_bf16 v[58:61], v[78:81], v[190:193], v[58:61]
	v_mfma_f32_16x16x32_bf16 v[46:49], v[70:73], v[198:201], v[46:49]
	v_mfma_f32_16x16x32_bf16 v[42:45], v[78:81], v[198:201], v[42:45]
	v_mfma_f32_16x16x32_bf16 v[30:33], v[70:73], v[206:209], v[30:33]
	v_mfma_f32_16x16x32_bf16 v[26:29], v[78:81], v[206:209], v[26:29]
	v_mfma_f32_16x16x32_bf16 v[14:17], v[70:73], v[220:223], v[14:17]
	v_mfma_f32_16x16x32_bf16 v[10:13], v[78:81], v[220:223], v[10:13]
	v_mfma_f32_16x16x32_bf16 v[54:57], v[82:85], v[186:189], v[54:57]
	v_mfma_f32_16x16x32_bf16 v[50:53], v[90:93], v[186:189], v[50:53]
	v_mfma_f32_16x16x32_bf16 v[38:41], v[82:85], v[194:197], v[38:41]
	v_mfma_f32_16x16x32_bf16 v[34:37], v[90:93], v[194:197], v[34:37]
	v_mfma_f32_16x16x32_bf16 v[22:25], v[82:85], v[202:205], v[22:25]
	v_mfma_f32_16x16x32_bf16 v[18:21], v[90:93], v[202:205], v[18:21]
	v_mfma_f32_16x16x32_bf16 v[6:9], v[82:85], v[216:219], v[6:9]
	v_mfma_f32_16x16x32_bf16 v[2:5], v[90:93], v[216:219], v[2:5]
	v_mfma_f32_16x16x32_bf16 v[54:57], v[86:89], v[190:193], v[54:57]
	v_mfma_f32_16x16x32_bf16 v[50:53], v[98:101], v[190:193], v[50:53]
	v_mfma_f32_16x16x32_bf16 v[38:41], v[86:89], v[198:201], v[38:41]
	v_mfma_f32_16x16x32_bf16 v[34:37], v[98:101], v[198:201], v[34:37]
	v_mfma_f32_16x16x32_bf16 v[22:25], v[86:89], v[206:209], v[22:25]
	v_mfma_f32_16x16x32_bf16 v[18:21], v[98:101], v[206:209], v[18:21]
	v_mfma_f32_16x16x32_bf16 v[6:9], v[86:89], v[220:223], v[6:9]
	v_mfma_f32_16x16x32_bf16 v[2:5], v[98:101], v[220:223], v[2:5]
	s_setprio 0
	s_barrier
	s_add_i32 s52, 0, 0x18000
	s_add_i32 s53, 0, 0x1c000
	v_add_u32_e32 v78, s52, v240
	v_add_u32_e32 v98, s53, v240
	ds_read_b128 v[66:69], v78
	ds_read_b128 v[70:73], v78 offset:1024
	ds_read_b128 v[74:77], v78 offset:2048
	ds_read_b128 v[78:81], v78 offset:3072
	ds_read_b128 v[82:85], v98
	ds_read_b128 v[86:89], v98 offset:1024
	ds_read_b128 v[90:93], v98 offset:2048
	ds_read_b128 v[98:101], v98 offset:3072
	s_add_u32 s34, s34, 0x80000
	s_addc_u32 s35, s35, 0
	s_mov_b32 m0, s43
	v_lshl_add_u64 v[228:229], s[34:35], 0, v[168:169]
	ds_read_b128 v[186:189], v241 offset:32768
	ds_read_b128 v[190:193], v241 offset:33792
	ds_read_b128 v[194:197], v241 offset:34816
	ds_read_b128 v[198:201], v241 offset:35840
	ds_read_b128 v[202:205], v241 offset:36864
	ds_read_b128 v[206:209], v241 offset:37888
	ds_read_b128 v[216:219], v241 offset:38912
	ds_read_b128 v[220:223], v241 offset:39936
	global_load_lds_dwordx4 v[228:229], off
	v_lshl_add_u64 v[228:229], s[34:35], 0, v[164:165]
	s_mov_b32 m0, s44
	s_nop 0
	global_load_lds_dwordx4 v[228:229], off
	s_waitcnt vmcnt(8) lgkmcnt(0)
	s_barrier
	s_setprio 1
	v_mfma_f32_16x16x32_bf16 v[158:161], v[66:69], v[186:189], v[158:161]
	v_mfma_f32_16x16x32_bf16 v[154:157], v[74:77], v[186:189], v[154:157]
	v_mfma_f32_16x16x32_bf16 v[142:145], v[66:69], v[194:197], v[142:145]
	v_mfma_f32_16x16x32_bf16 v[138:141], v[74:77], v[194:197], v[138:141]
	v_mfma_f32_16x16x32_bf16 v[126:129], v[66:69], v[202:205], v[126:129]
	v_mfma_f32_16x16x32_bf16 v[122:125], v[74:77], v[202:205], v[122:125]
	v_mfma_f32_16x16x32_bf16 v[110:113], v[66:69], v[216:219], v[110:113]
	v_mfma_f32_16x16x32_bf16 v[106:109], v[74:77], v[216:219], v[106:109]
	v_mfma_f32_16x16x32_bf16 v[158:161], v[70:73], v[190:193], v[158:161]
	v_mfma_f32_16x16x32_bf16 v[154:157], v[78:81], v[190:193], v[154:157]
	v_mfma_f32_16x16x32_bf16 v[142:145], v[70:73], v[198:201], v[142:145]
	v_mfma_f32_16x16x32_bf16 v[138:141], v[78:81], v[198:201], v[138:141]
	v_mfma_f32_16x16x32_bf16 v[126:129], v[70:73], v[206:209], v[126:129]
	v_mfma_f32_16x16x32_bf16 v[122:125], v[78:81], v[206:209], v[122:125]
	v_mfma_f32_16x16x32_bf16 v[110:113], v[70:73], v[220:223], v[110:113]
	v_mfma_f32_16x16x32_bf16 v[106:109], v[78:81], v[220:223], v[106:109]
	v_mfma_f32_16x16x32_bf16 v[150:153], v[82:85], v[186:189], v[150:153]
	v_mfma_f32_16x16x32_bf16 v[146:149], v[90:93], v[186:189], v[146:149]
	v_mfma_f32_16x16x32_bf16 v[134:137], v[82:85], v[194:197], v[134:137]
	v_mfma_f32_16x16x32_bf16 v[130:133], v[90:93], v[194:197], v[130:133]
	v_mfma_f32_16x16x32_bf16 v[118:121], v[82:85], v[202:205], v[118:121]
	v_mfma_f32_16x16x32_bf16 v[114:117], v[90:93], v[202:205], v[114:117]
	v_mfma_f32_16x16x32_bf16 v[102:105], v[82:85], v[216:219], v[102:105]
	v_mfma_f32_16x16x32_bf16 v[94:97], v[90:93], v[216:219], v[94:97]
	v_mfma_f32_16x16x32_bf16 v[150:153], v[86:89], v[190:193], v[150:153]
	v_mfma_f32_16x16x32_bf16 v[146:149], v[98:101], v[190:193], v[146:149]
	v_mfma_f32_16x16x32_bf16 v[134:137], v[86:89], v[198:201], v[134:137]
	v_mfma_f32_16x16x32_bf16 v[130:133], v[98:101], v[198:201], v[130:133]
	v_mfma_f32_16x16x32_bf16 v[118:121], v[86:89], v[206:209], v[118:121]
	v_mfma_f32_16x16x32_bf16 v[114:117], v[98:101], v[206:209], v[114:117]
	v_mfma_f32_16x16x32_bf16 v[102:105], v[86:89], v[220:223], v[102:105]
	v_mfma_f32_16x16x32_bf16 v[94:97], v[98:101], v[220:223], v[94:97]
	s_setprio 0
	s_barrier
	s_add_i32 s34, s52, s36
	v_lshl_add_u64 v[212:213], v[212:213], 0, s[64:65]
	s_mov_b32 m0, s34
	ds_read_b128 v[186:189], v241 offset:49152
	ds_read_b128 v[190:193], v241 offset:50176
	ds_read_b128 v[194:197], v241 offset:51200
	ds_read_b128 v[198:201], v241 offset:52224
	ds_read_b128 v[202:205], v241 offset:53248
	ds_read_b128 v[206:209], v241 offset:54272
	ds_read_b128 v[216:219], v241 offset:55296
	ds_read_b128 v[220:223], v241 offset:56320
	global_load_lds_dwordx4 v[212:213], off
	s_add_i32 m0, s34, 0x2000
	s_add_u32 s30, s30, 0x80080
	v_lshl_add_u64 v[212:213], v[214:215], 0, s[64:65]
	s_addc_u32 s31, s31, 0
	s_add_i32 s34, s53, s36
	global_load_lds_dwordx4 v[212:213], off
	v_lshl_add_u64 v[212:213], s[30:31], 0, v[166:167]
	s_mov_b32 m0, s34
	s_nop 0
	global_load_lds_dwordx4 v[212:213], off
	v_lshl_add_u64 v[212:213], s[30:31], 0, v[162:163]
	s_add_i32 m0, s34, 0x2000
	s_nop 0
	global_load_lds_dwordx4 v[212:213], off
	v_lshl_add_u64 v[212:213], v[224:225], 0, s[64:65]
	s_mov_b32 m0, s46
	s_nop 0
	global_load_lds_dwordx4 v[212:213], off
	v_lshl_add_u64 v[212:213], v[226:227], 0, s[64:65]
	s_mov_b32 m0, s47
	s_nop 0
	global_load_lds_dwordx4 v[212:213], off
	s_waitcnt vmcnt(8) lgkmcnt(0)
	s_barrier
	s_setprio 1
	v_mfma_f32_16x16x32_bf16 v[62:65], v[66:69], v[186:189], v[62:65]
	v_mfma_f32_16x16x32_bf16 v[58:61], v[74:77], v[186:189], v[58:61]
	v_mfma_f32_16x16x32_bf16 v[46:49], v[66:69], v[194:197], v[46:49]
	v_mfma_f32_16x16x32_bf16 v[42:45], v[74:77], v[194:197], v[42:45]
	v_mfma_f32_16x16x32_bf16 v[30:33], v[66:69], v[202:205], v[30:33]
	v_mfma_f32_16x16x32_bf16 v[26:29], v[74:77], v[202:205], v[26:29]
	v_mfma_f32_16x16x32_bf16 v[14:17], v[66:69], v[216:219], v[14:17]
	v_mfma_f32_16x16x32_bf16 v[10:13], v[74:77], v[216:219], v[10:13]
	v_mfma_f32_16x16x32_bf16 v[62:65], v[70:73], v[190:193], v[62:65]
	v_mfma_f32_16x16x32_bf16 v[58:61], v[78:81], v[190:193], v[58:61]
	v_mfma_f32_16x16x32_bf16 v[46:49], v[70:73], v[198:201], v[46:49]
	v_mfma_f32_16x16x32_bf16 v[42:45], v[78:81], v[198:201], v[42:45]
	v_mfma_f32_16x16x32_bf16 v[30:33], v[70:73], v[206:209], v[30:33]
	v_mfma_f32_16x16x32_bf16 v[26:29], v[78:81], v[206:209], v[26:29]
	v_mfma_f32_16x16x32_bf16 v[14:17], v[70:73], v[220:223], v[14:17]
	v_mfma_f32_16x16x32_bf16 v[10:13], v[78:81], v[220:223], v[10:13]
	v_mfma_f32_16x16x32_bf16 v[54:57], v[82:85], v[186:189], v[54:57]
	v_mfma_f32_16x16x32_bf16 v[50:53], v[90:93], v[186:189], v[50:53]
	v_mfma_f32_16x16x32_bf16 v[38:41], v[82:85], v[194:197], v[38:41]
	v_mfma_f32_16x16x32_bf16 v[34:37], v[90:93], v[194:197], v[34:37]
	v_mfma_f32_16x16x32_bf16 v[22:25], v[82:85], v[202:205], v[22:25]
	v_mfma_f32_16x16x32_bf16 v[18:21], v[90:93], v[202:205], v[18:21]
	v_mfma_f32_16x16x32_bf16 v[6:9], v[82:85], v[216:219], v[6:9]
	v_mfma_f32_16x16x32_bf16 v[2:5], v[90:93], v[216:219], v[2:5]
	v_mfma_f32_16x16x32_bf16 v[54:57], v[86:89], v[190:193], v[54:57]
	v_mfma_f32_16x16x32_bf16 v[50:53], v[98:101], v[190:193], v[50:53]
	v_mfma_f32_16x16x32_bf16 v[38:41], v[86:89], v[198:201], v[38:41]
	v_mfma_f32_16x16x32_bf16 v[34:37], v[98:101], v[198:201], v[34:37]
	v_mfma_f32_16x16x32_bf16 v[22:25], v[86:89], v[206:209], v[22:25]
	v_mfma_f32_16x16x32_bf16 v[18:21], v[98:101], v[206:209], v[18:21]
	v_mfma_f32_16x16x32_bf16 v[6:9], v[86:89], v[220:223], v[6:9]
	v_mfma_f32_16x16x32_bf16 v[2:5], v[98:101], v[220:223], v[2:5]
	s_setprio 0
	s_barrier
	s_add_i32 s51, s51, 2
	s_add_u32 s6, s6, 0x100
	s_addc_u32 s7, s7, 0
	s_add_u32 s49, s49, 0x100
	s_addc_u32 s50, s50, 0
	s_cmp_gt_u32 s51, 29
	s_cbranch_scc0 .LBB0_116
	s_and_b64 vcc, exec, s[18:19]
	s_cbranch_vccz .LBB0_119
	s_barrier

.LBB0_226:
	s_add_u32 s30, s8, 0xfff80080
	s_addc_u32 s31, s9, -1
	s_add_i32 s54, 0, 0x10000
	s_cmp_eq_u32 s53, 28
	s_cselect_b32 s35, s23, s31
	s_cselect_b32 s34, s28, s30
	s_cselect_b32 s31, s21, s52
	s_cselect_b32 s30, s29, s51
	s_add_i32 s56, 0, 0x14000
	v_add_u32_e32 v160, s54, v141
	v_add_u32_e32 v176, s56, v141
	ds_read_b128 v[148:151], v160
	ds_read_b128 v[152:155], v160 offset:1024
	ds_read_b128 v[156:159], v160 offset:2048
	ds_read_b128 v[160:163], v160 offset:3072
	ds_read_b128 v[164:167], v176
	ds_read_b128 v[168:171], v176 offset:1024
	ds_read_b128 v[172:175], v176 offset:2048
	ds_read_b128 v[176:179], v176 offset:3072
	v_lshl_add_u64 v[208:209], s[8:9], 0, v[144:145]
	s_add_i32 m0, s41, 0xc000
	ds_read_b128 v[180:183], v238
	ds_read_b128 v[184:187], v238 offset:1024
	ds_read_b128 v[188:191], v238 offset:2048
	ds_read_b128 v[192:195], v238 offset:3072
	ds_read_b128 v[196:199], v238 offset:4096
	ds_read_b128 v[200:203], v238 offset:5120
	ds_read_b128 v[204:207], v238 offset:6144
	ds_read_b128 v[216:219], v238 offset:7168
	global_load_lds_dwordx4 v[208:209], off
	v_lshl_add_u64 v[208:209], s[8:9], 0, v[146:147]
	s_add_i32 m0, s41, 0xe000
	s_nop 0
	global_load_lds_dwordx4 v[208:209], off
	s_waitcnt vmcnt(8) lgkmcnt(0)
	s_barrier
	s_setprio 1
	v_mfma_f32_16x16x32_bf16 v[126:129], v[148:151], v[180:183], v[126:129]
	v_mfma_f32_16x16x32_bf16 v[122:125], v[156:159], v[180:183], v[122:125]
	v_mfma_f32_16x16x32_bf16 v[110:113], v[148:151], v[188:191], v[110:113]
	v_mfma_f32_16x16x32_bf16 v[106:109], v[156:159], v[188:191], v[106:109]
	v_mfma_f32_16x16x32_bf16 v[94:97], v[148:151], v[196:199], v[94:97]
	v_mfma_f32_16x16x32_bf16 v[90:93], v[156:159], v[196:199], v[90:93]
	v_mfma_f32_16x16x32_bf16 v[78:81], v[148:151], v[204:207], v[78:81]
	v_mfma_f32_16x16x32_bf16 v[74:77], v[156:159], v[204:207], v[74:77]
	v_mfma_f32_16x16x32_bf16 v[126:129], v[152:155], v[184:187], v[126:129]
	v_mfma_f32_16x16x32_bf16 v[122:125], v[160:163], v[184:187], v[122:125]
	v_mfma_f32_16x16x32_bf16 v[110:113], v[152:155], v[192:195], v[110:113]
	v_mfma_f32_16x16x32_bf16 v[106:109], v[160:163], v[192:195], v[106:109]
	v_mfma_f32_16x16x32_bf16 v[94:97], v[152:155], v[200:203], v[94:97]
	v_mfma_f32_16x16x32_bf16 v[90:93], v[160:163], v[200:203], v[90:93]
	v_mfma_f32_16x16x32_bf16 v[78:81], v[152:155], v[216:219], v[78:81]
	v_mfma_f32_16x16x32_bf16 v[74:77], v[160:163], v[216:219], v[74:77]
	v_mfma_f32_16x16x32_bf16 v[118:121], v[164:167], v[180:183], v[118:121]
	v_mfma_f32_16x16x32_bf16 v[114:117], v[172:175], v[180:183], v[114:117]
	v_mfma_f32_16x16x32_bf16 v[102:105], v[164:167], v[188:191], v[102:105]
	v_mfma_f32_16x16x32_bf16 v[98:101], v[172:175], v[188:191], v[98:101]
	v_mfma_f32_16x16x32_bf16 v[86:89], v[164:167], v[196:199], v[86:89]
	v_mfma_f32_16x16x32_bf16 v[82:85], v[172:175], v[196:199], v[82:85]
	v_mfma_f32_16x16x32_bf16 v[70:73], v[164:167], v[204:207], v[70:73]
	v_mfma_f32_16x16x32_bf16 v[66:69], v[172:175], v[204:207], v[66:69]
	v_mfma_f32_16x16x32_bf16 v[118:121], v[168:171], v[184:187], v[118:121]
	v_mfma_f32_16x16x32_bf16 v[114:117], v[176:179], v[184:187], v[114:117]
	v_mfma_f32_16x16x32_bf16 v[102:105], v[168:171], v[192:195], v[102:105]
	v_mfma_f32_16x16x32_bf16 v[98:101], v[176:179], v[192:195], v[98:101]
	v_mfma_f32_16x16x32_bf16 v[86:89], v[168:171], v[200:203], v[86:89]
	v_mfma_f32_16x16x32_bf16 v[82:85], v[176:179], v[200:203], v[82:85]
	v_mfma_f32_16x16x32_bf16 v[70:73], v[168:171], v[216:219], v[70:73]
	v_mfma_f32_16x16x32_bf16 v[66:69], v[176:179], v[216:219], v[66:69]
	s_setprio 0
	s_barrier
	s_add_i32 s54, s54, s40
	v_lshl_add_u64 v[208:209], s[30:31], 0, v[134:135]
	s_mov_b32 m0, s54
	ds_read_b128 v[180:183], v238 offset:16384
	ds_read_b128 v[184:187], v238 offset:17408
	ds_read_b128 v[188:191], v238 offset:18432
	ds_read_b128 v[192:195], v238 offset:19456
	ds_read_b128 v[196:199], v238 offset:20480
	ds_read_b128 v[200:203], v238 offset:21504
	ds_read_b128 v[204:207], v238 offset:22528
	ds_read_b128 v[216:219], v238 offset:23552
	global_load_lds_dwordx4 v[208:209], off
	s_add_i32 m0, s54, 0x2000
	s_add_u32 s54, s30, 0x80000
	v_lshl_add_u64 v[212:213], s[30:31], 0, v[130:131]
	s_addc_u32 s55, s31, 0
	s_add_i32 s56, s56, s40
	global_load_lds_dwordx4 v[212:213], off
	v_lshl_add_u64 v[214:215], s[54:55], 0, v[134:135]
	s_mov_b32 m0, s56
	v_lshl_add_u64 v[220:221], s[34:35], 0, v[132:133]
	global_load_lds_dwordx4 v[214:215], off
	v_lshl_add_u64 v[214:215], s[54:55], 0, v[130:131]
	s_add_i32 m0, s56, 0x2000
	s_nop 0
	global_load_lds_dwordx4 v[214:215], off
	v_lshl_add_u64 v[214:215], s[34:35], 0, v[136:137]
	s_mov_b32 m0, s41
	s_nop 0
	global_load_lds_dwordx4 v[214:215], off
	s_mov_b32 m0, s42
	s_nop 0
	global_load_lds_dwordx4 v[220:221], off
	s_waitcnt vmcnt(8) lgkmcnt(0)
	s_barrier
	s_setprio 1
	v_mfma_f32_16x16x32_bf16 v[62:65], v[148:151], v[180:183], v[62:65]
	v_mfma_f32_16x16x32_bf16 v[58:61], v[156:159], v[180:183], v[58:61]
	v_mfma_f32_16x16x32_bf16 v[46:49], v[148:151], v[188:191], v[46:49]
	v_mfma_f32_16x16x32_bf16 v[42:45], v[156:159], v[188:191], v[42:45]
	v_mfma_f32_16x16x32_bf16 v[30:33], v[148:151], v[196:199], v[30:33]
	v_mfma_f32_16x16x32_bf16 v[26:29], v[156:159], v[196:199], v[26:29]
	v_mfma_f32_16x16x32_bf16 v[14:17], v[148:151], v[204:207], v[14:17]
	v_mfma_f32_16x16x32_bf16 v[10:13], v[156:159], v[204:207], v[10:13]
	v_mfma_f32_16x16x32_bf16 v[62:65], v[152:155], v[184:187], v[62:65]
	v_mfma_f32_16x16x32_bf16 v[58:61], v[160:163], v[184:187], v[58:61]
	v_mfma_f32_16x16x32_bf16 v[46:49], v[152:155], v[192:195], v[46:49]
	v_mfma_f32_16x16x32_bf16 v[42:45], v[160:163], v[192:195], v[42:45]
	v_mfma_f32_16x16x32_bf16 v[30:33], v[152:155], v[200:203], v[30:33]
	v_mfma_f32_16x16x32_bf16 v[26:29], v[160:163], v[200:203], v[26:29]
	v_mfma_f32_16x16x32_bf16 v[14:17], v[152:155], v[216:219], v[14:17]
	v_mfma_f32_16x16x32_bf16 v[10:13], v[160:163], v[216:219], v[10:13]
	v_mfma_f32_16x16x32_bf16 v[54:57], v[164:167], v[180:183], v[54:57]
	v_mfma_f32_16x16x32_bf16 v[50:53], v[172:175], v[180:183], v[50:53]
	v_mfma_f32_16x16x32_bf16 v[38:41], v[164:167], v[188:191], v[38:41]
	v_mfma_f32_16x16x32_bf16 v[34:37], v[172:175], v[188:191], v[34:37]
	v_mfma_f32_16x16x32_bf16 v[22:25], v[164:167], v[196:199], v[22:25]
	v_mfma_f32_16x16x32_bf16 v[18:21], v[172:175], v[196:199], v[18:21]
	v_mfma_f32_16x16x32_bf16 v[6:9], v[164:167], v[204:207], v[6:9]
	v_mfma_f32_16x16x32_bf16 v[2:5], v[172:175], v[204:207], v[2:5]
	v_mfma_f32_16x16x32_bf16 v[54:57], v[168:171], v[184:187], v[54:57]
	v_mfma_f32_16x16x32_bf16 v[50:53], v[176:179], v[184:187], v[50:53]
	v_mfma_f32_16x16x32_bf16 v[38:41], v[168:171], v[192:195], v[38:41]
	v_mfma_f32_16x16x32_bf16 v[34:37], v[176:179], v[192:195], v[34:37]
	v_mfma_f32_16x16x32_bf16 v[22:25], v[168:171], v[200:203], v[22:25]
	v_mfma_f32_16x16x32_bf16 v[18:21], v[176:179], v[200:203], v[18:21]
	v_mfma_f32_16x16x32_bf16 v[6:9], v[168:171], v[216:219], v[6:9]
	v_mfma_f32_16x16x32_bf16 v[2:5], v[176:179], v[216:219], v[2:5]
	s_setprio 0
	s_barrier
	s_add_i32 s54, 0, 0x18000
	s_add_i32 s55, 0, 0x1c000
	v_add_u32_e32 v160, s54, v141
	v_add_u32_e32 v176, s55, v141
	ds_read_b128 v[148:151], v160
	ds_read_b128 v[152:155], v160 offset:1024
	ds_read_b128 v[156:159], v160 offset:2048
	ds_read_b128 v[160:163], v160 offset:3072
	ds_read_b128 v[164:167], v176
	ds_read_b128 v[168:171], v176 offset:1024
	ds_read_b128 v[172:175], v176 offset:2048
	ds_read_b128 v[176:179], v176 offset:3072
	s_add_u32 s34, s34, 0x80000
	s_addc_u32 s35, s35, 0
	s_mov_b32 m0, s43
	v_lshl_add_u64 v[222:223], s[34:35], 0, v[136:137]
	ds_read_b128 v[180:183], v238 offset:32768
	ds_read_b128 v[184:187], v238 offset:33792
	ds_read_b128 v[188:191], v238 offset:34816
	ds_read_b128 v[192:195], v238 offset:35840
	ds_read_b128 v[196:199], v238 offset:36864
	ds_read_b128 v[200:203], v238 offset:37888
	ds_read_b128 v[204:207], v238 offset:38912
	ds_read_b128 v[216:219], v238 offset:39936
	global_load_lds_dwordx4 v[222:223], off
	v_lshl_add_u64 v[222:223], s[34:35], 0, v[132:133]
	s_mov_b32 m0, s44
	s_nop 0
	global_load_lds_dwordx4 v[222:223], off
	s_waitcnt vmcnt(8) lgkmcnt(0)
	s_barrier
	s_setprio 1
	v_mfma_f32_16x16x32_bf16 v[126:129], v[148:151], v[180:183], v[126:129]
	v_mfma_f32_16x16x32_bf16 v[122:125], v[156:159], v[180:183], v[122:125]
	v_mfma_f32_16x16x32_bf16 v[110:113], v[148:151], v[188:191], v[110:113]
	v_mfma_f32_16x16x32_bf16 v[106:109], v[156:159], v[188:191], v[106:109]
	v_mfma_f32_16x16x32_bf16 v[94:97], v[148:151], v[196:199], v[94:97]
	v_mfma_f32_16x16x32_bf16 v[90:93], v[156:159], v[196:199], v[90:93]
	v_mfma_f32_16x16x32_bf16 v[78:81], v[148:151], v[204:207], v[78:81]
	v_mfma_f32_16x16x32_bf16 v[74:77], v[156:159], v[204:207], v[74:77]
	v_mfma_f32_16x16x32_bf16 v[126:129], v[152:155], v[184:187], v[126:129]
	v_mfma_f32_16x16x32_bf16 v[122:125], v[160:163], v[184:187], v[122:125]
	v_mfma_f32_16x16x32_bf16 v[110:113], v[152:155], v[192:195], v[110:113]
	v_mfma_f32_16x16x32_bf16 v[106:109], v[160:163], v[192:195], v[106:109]
	v_mfma_f32_16x16x32_bf16 v[94:97], v[152:155], v[200:203], v[94:97]
	v_mfma_f32_16x16x32_bf16 v[90:93], v[160:163], v[200:203], v[90:93]
	v_mfma_f32_16x16x32_bf16 v[78:81], v[152:155], v[216:219], v[78:81]
	v_mfma_f32_16x16x32_bf16 v[74:77], v[160:163], v[216:219], v[74:77]
	v_mfma_f32_16x16x32_bf16 v[118:121], v[164:167], v[180:183], v[118:121]
	v_mfma_f32_16x16x32_bf16 v[114:117], v[172:175], v[180:183], v[114:117]
	v_mfma_f32_16x16x32_bf16 v[102:105], v[164:167], v[188:191], v[102:105]
	v_mfma_f32_16x16x32_bf16 v[98:101], v[172:175], v[188:191], v[98:101]
	v_mfma_f32_16x16x32_bf16 v[86:89], v[164:167], v[196:199], v[86:89]
	v_mfma_f32_16x16x32_bf16 v[82:85], v[172:175], v[196:199], v[82:85]
	v_mfma_f32_16x16x32_bf16 v[70:73], v[164:167], v[204:207], v[70:73]
	v_mfma_f32_16x16x32_bf16 v[66:69], v[172:175], v[204:207], v[66:69]
	v_mfma_f32_16x16x32_bf16 v[118:121], v[168:171], v[184:187], v[118:121]
	v_mfma_f32_16x16x32_bf16 v[114:117], v[176:179], v[184:187], v[114:117]
	v_mfma_f32_16x16x32_bf16 v[102:105], v[168:171], v[192:195], v[102:105]
	v_mfma_f32_16x16x32_bf16 v[98:101], v[176:179], v[192:195], v[98:101]
	v_mfma_f32_16x16x32_bf16 v[86:89], v[168:171], v[200:203], v[86:89]
	v_mfma_f32_16x16x32_bf16 v[82:85], v[176:179], v[200:203], v[82:85]
	v_mfma_f32_16x16x32_bf16 v[70:73], v[168:171], v[216:219], v[70:73]
	v_mfma_f32_16x16x32_bf16 v[66:69], v[176:179], v[216:219], v[66:69]
	s_setprio 0
	s_barrier
	s_add_i32 s34, s54, s40
	v_lshl_add_u64 v[208:209], v[208:209], 0, s[64:65]
	s_mov_b32 m0, s34
	ds_read_b128 v[180:183], v238 offset:49152
	ds_read_b128 v[184:187], v238 offset:50176
	ds_read_b128 v[188:191], v238 offset:51200
	ds_read_b128 v[192:195], v238 offset:52224
	ds_read_b128 v[196:199], v238 offset:53248
	ds_read_b128 v[200:203], v238 offset:54272
	ds_read_b128 v[204:207], v238 offset:55296
	ds_read_b128 v[216:219], v238 offset:56320
	global_load_lds_dwordx4 v[208:209], off
	s_add_i32 m0, s34, 0x2000
	s_add_u32 s30, s30, 0x80080
	v_lshl_add_u64 v[208:209], v[212:213], 0, s[64:65]
	s_addc_u32 s31, s31, 0
	s_add_i32 s34, s55, s40
	global_load_lds_dwordx4 v[208:209], off
	v_lshl_add_u64 v[208:209], s[30:31], 0, v[134:135]
	s_mov_b32 m0, s34
	s_nop 0
	global_load_lds_dwordx4 v[208:209], off
	v_lshl_add_u64 v[208:209], s[30:31], 0, v[130:131]
	s_add_i32 m0, s34, 0x2000
	s_nop 0
	global_load_lds_dwordx4 v[208:209], off
	v_lshl_add_u64 v[208:209], v[214:215], 0, s[64:65]
	s_mov_b32 m0, s46
	s_nop 0
	global_load_lds_dwordx4 v[208:209], off
	v_lshl_add_u64 v[208:209], v[220:221], 0, s[64:65]
	s_mov_b32 m0, s47
	s_nop 0
	global_load_lds_dwordx4 v[208:209], off
	s_waitcnt vmcnt(8) lgkmcnt(0)
	s_barrier
	s_setprio 1
	v_mfma_f32_16x16x32_bf16 v[62:65], v[148:151], v[180:183], v[62:65]
	v_mfma_f32_16x16x32_bf16 v[58:61], v[156:159], v[180:183], v[58:61]
	v_mfma_f32_16x16x32_bf16 v[46:49], v[148:151], v[188:191], v[46:49]
	v_mfma_f32_16x16x32_bf16 v[42:45], v[156:159], v[188:191], v[42:45]
	v_mfma_f32_16x16x32_bf16 v[30:33], v[148:151], v[196:199], v[30:33]
	v_mfma_f32_16x16x32_bf16 v[26:29], v[156:159], v[196:199], v[26:29]
	v_mfma_f32_16x16x32_bf16 v[14:17], v[148:151], v[204:207], v[14:17]
	v_mfma_f32_16x16x32_bf16 v[10:13], v[156:159], v[204:207], v[10:13]
	v_mfma_f32_16x16x32_bf16 v[62:65], v[152:155], v[184:187], v[62:65]
	v_mfma_f32_16x16x32_bf16 v[58:61], v[160:163], v[184:187], v[58:61]
	v_mfma_f32_16x16x32_bf16 v[46:49], v[152:155], v[192:195], v[46:49]
	v_mfma_f32_16x16x32_bf16 v[42:45], v[160:163], v[192:195], v[42:45]
	v_mfma_f32_16x16x32_bf16 v[30:33], v[152:155], v[200:203], v[30:33]
	v_mfma_f32_16x16x32_bf16 v[26:29], v[160:163], v[200:203], v[26:29]
	v_mfma_f32_16x16x32_bf16 v[14:17], v[152:155], v[216:219], v[14:17]
	v_mfma_f32_16x16x32_bf16 v[10:13], v[160:163], v[216:219], v[10:13]
	v_mfma_f32_16x16x32_bf16 v[54:57], v[164:167], v[180:183], v[54:57]
	v_mfma_f32_16x16x32_bf16 v[50:53], v[172:175], v[180:183], v[50:53]
	v_mfma_f32_16x16x32_bf16 v[38:41], v[164:167], v[188:191], v[38:41]
	v_mfma_f32_16x16x32_bf16 v[34:37], v[172:175], v[188:191], v[34:37]
	v_mfma_f32_16x16x32_bf16 v[22:25], v[164:167], v[196:199], v[22:25]
	v_mfma_f32_16x16x32_bf16 v[18:21], v[172:175], v[196:199], v[18:21]
	v_mfma_f32_16x16x32_bf16 v[6:9], v[164:167], v[204:207], v[6:9]
	v_mfma_f32_16x16x32_bf16 v[2:5], v[172:175], v[204:207], v[2:5]
	v_mfma_f32_16x16x32_bf16 v[54:57], v[168:171], v[184:187], v[54:57]
	v_mfma_f32_16x16x32_bf16 v[50:53], v[176:179], v[184:187], v[50:53]
	v_mfma_f32_16x16x32_bf16 v[38:41], v[168:171], v[192:195], v[38:41]
	v_mfma_f32_16x16x32_bf16 v[34:37], v[176:179], v[192:195], v[34:37]
	v_mfma_f32_16x16x32_bf16 v[22:25], v[168:171], v[200:203], v[22:25]
	v_mfma_f32_16x16x32_bf16 v[18:21], v[176:179], v[200:203], v[18:21]
	v_mfma_f32_16x16x32_bf16 v[6:9], v[168:171], v[216:219], v[6:9]
	v_mfma_f32_16x16x32_bf16 v[2:5], v[176:179], v[216:219], v[2:5]
	s_setprio 0
	s_barrier
	s_add_i32 s53, s53, 2
	s_add_u32 s8, s8, 0x100
	s_addc_u32 s9, s9, 0
	s_add_u32 s51, s51, 0x100
	s_addc_u32 s52, s52, 0
	s_cmp_gt_u32 s53, 29
	s_cbranch_scc0 .LBB0_226
	s_and_b64 vcc, exec, s[18:19]
	s_cbranch_vccz .LBB0_229
	s_barrier

.LBB0_956:
	s_add_u32 s10, s34, 0x100
	s_addc_u32 s11, s35, 0
	s_add_i32 s63, 0, 0x10000
	s_cmp_eq_u32 s62, 28
	s_cselect_b32 s47, s2, s11
	s_cselect_b32 s46, s3, s10
	s_cselect_b32 s43, s31, s61
	s_cselect_b32 s42, s37, s60
	s_add_i32 s66, 0, 0x14000
	v_add_u32_e32 v78, s63, v251
	v_add_u32_e32 v94, s66, v251
	ds_read_b128 v[66:69], v78
	ds_read_b128 v[70:73], v78 offset:1024
	ds_read_b128 v[74:77], v78 offset:2048
	ds_read_b128 v[78:81], v78 offset:3072
	ds_read_b128 v[82:85], v94
	ds_read_b128 v[86:89], v94 offset:1024
	ds_read_b128 v[90:93], v94 offset:2048
	ds_read_b128 v[94:97], v94 offset:3072
	v_lshl_add_u64 v[194:195], s[34:35], 0, v[218:219]
	s_add_i32 m0, s51, 0xc000
	ds_read_b128 v[162:165], v244
	ds_read_b128 v[166:169], v244 offset:1024
	ds_read_b128 v[170:173], v244 offset:2048
	ds_read_b128 v[174:177], v244 offset:3072
	ds_read_b128 v[178:181], v244 offset:4096
	ds_read_b128 v[182:185], v244 offset:5120
	ds_read_b128 v[186:189], v244 offset:6144
	ds_read_b128 v[190:193], v244 offset:7168
	global_load_lds_dwordx4 v[194:195], off
	v_lshl_add_u64 v[194:195], s[34:35], 0, v[220:221]
	s_add_i32 m0, s51, 0xe000
	s_nop 0
	global_load_lds_dwordx4 v[194:195], off
	s_waitcnt vmcnt(8) lgkmcnt(0)
	s_barrier
	s_setprio 1
	v_mfma_f32_16x16x32_bf16 v[158:161], v[66:69], v[162:165], v[158:161]
	v_mfma_f32_16x16x32_bf16 v[154:157], v[74:77], v[162:165], v[154:157]
	v_mfma_f32_16x16x32_bf16 v[142:145], v[66:69], v[170:173], v[142:145]
	v_mfma_f32_16x16x32_bf16 v[138:141], v[74:77], v[170:173], v[138:141]
	v_mfma_f32_16x16x32_bf16 v[126:129], v[66:69], v[178:181], v[126:129]
	v_mfma_f32_16x16x32_bf16 v[122:125], v[74:77], v[178:181], v[122:125]
	v_mfma_f32_16x16x32_bf16 v[110:113], v[66:69], v[186:189], v[110:113]
	v_mfma_f32_16x16x32_bf16 v[106:109], v[74:77], v[186:189], v[106:109]
	v_mfma_f32_16x16x32_bf16 v[158:161], v[70:73], v[166:169], v[158:161]
	v_mfma_f32_16x16x32_bf16 v[154:157], v[78:81], v[166:169], v[154:157]
	v_mfma_f32_16x16x32_bf16 v[142:145], v[70:73], v[174:177], v[142:145]
	v_mfma_f32_16x16x32_bf16 v[138:141], v[78:81], v[174:177], v[138:141]
	v_mfma_f32_16x16x32_bf16 v[126:129], v[70:73], v[182:185], v[126:129]
	v_mfma_f32_16x16x32_bf16 v[122:125], v[78:81], v[182:185], v[122:125]
	v_mfma_f32_16x16x32_bf16 v[110:113], v[70:73], v[190:193], v[110:113]
	v_mfma_f32_16x16x32_bf16 v[106:109], v[78:81], v[190:193], v[106:109]
	v_mfma_f32_16x16x32_bf16 v[150:153], v[82:85], v[162:165], v[150:153]
	v_mfma_f32_16x16x32_bf16 v[146:149], v[90:93], v[162:165], v[146:149]
	v_mfma_f32_16x16x32_bf16 v[134:137], v[82:85], v[170:173], v[134:137]
	v_mfma_f32_16x16x32_bf16 v[130:133], v[90:93], v[170:173], v[130:133]
	v_mfma_f32_16x16x32_bf16 v[118:121], v[82:85], v[178:181], v[118:121]
	v_mfma_f32_16x16x32_bf16 v[114:117], v[90:93], v[178:181], v[114:117]
	v_mfma_f32_16x16x32_bf16 v[102:105], v[82:85], v[186:189], v[102:105]
	v_mfma_f32_16x16x32_bf16 v[98:101], v[90:93], v[186:189], v[98:101]
	v_mfma_f32_16x16x32_bf16 v[150:153], v[86:89], v[166:169], v[150:153]
	v_mfma_f32_16x16x32_bf16 v[146:149], v[94:97], v[166:169], v[146:149]
	v_mfma_f32_16x16x32_bf16 v[134:137], v[86:89], v[174:177], v[134:137]
	v_mfma_f32_16x16x32_bf16 v[130:133], v[94:97], v[174:177], v[130:133]
	v_mfma_f32_16x16x32_bf16 v[118:121], v[86:89], v[182:185], v[118:121]
	v_mfma_f32_16x16x32_bf16 v[114:117], v[94:97], v[182:185], v[114:117]
	v_mfma_f32_16x16x32_bf16 v[102:105], v[86:89], v[190:193], v[102:105]
	v_mfma_f32_16x16x32_bf16 v[98:101], v[94:97], v[190:193], v[98:101]
	s_setprio 0
	s_barrier
	s_add_i32 s34, s63, s44
	v_lshl_add_u64 v[194:195], s[42:43], 0, v[210:211]
	s_mov_b32 m0, s34
	ds_read_b128 v[162:165], v244 offset:16384
	ds_read_b128 v[166:169], v244 offset:17408
	ds_read_b128 v[170:173], v244 offset:18432
	ds_read_b128 v[174:177], v244 offset:19456
	ds_read_b128 v[178:181], v244 offset:20480
	ds_read_b128 v[182:185], v244 offset:21504
	ds_read_b128 v[186:189], v244 offset:22528
	ds_read_b128 v[190:193], v244 offset:23552
	global_load_lds_dwordx4 v[194:195], off
	s_add_i32 m0, s34, 0x2000
	s_add_u32 s34, s42, 0x80000
	v_lshl_add_u64 v[196:197], s[42:43], 0, v[216:217]
	s_addc_u32 s35, s43, 0
	s_add_i32 s63, s66, s44
	global_load_lds_dwordx4 v[196:197], off
	v_lshl_add_u64 v[198:199], s[34:35], 0, v[210:211]
	s_mov_b32 m0, s63
	v_lshl_add_u64 v[200:201], s[46:47], 0, v[216:217]
	global_load_lds_dwordx4 v[198:199], off
	v_lshl_add_u64 v[198:199], s[34:35], 0, v[216:217]
	s_add_i32 m0, s63, 0x2000
	s_nop 0
	global_load_lds_dwordx4 v[198:199], off
	v_lshl_add_u64 v[198:199], s[46:47], 0, v[210:211]
	s_mov_b32 m0, s51
	s_nop 0
	global_load_lds_dwordx4 v[198:199], off
	s_mov_b32 m0, s52
	s_nop 0
	global_load_lds_dwordx4 v[200:201], off
	s_waitcnt vmcnt(8) lgkmcnt(0)
	s_barrier
	s_setprio 1
	v_mfma_f32_16x16x32_bf16 v[62:65], v[66:69], v[162:165], v[62:65]
	v_mfma_f32_16x16x32_bf16 v[58:61], v[74:77], v[162:165], v[58:61]
	v_mfma_f32_16x16x32_bf16 v[46:49], v[66:69], v[170:173], v[46:49]
	v_mfma_f32_16x16x32_bf16 v[42:45], v[74:77], v[170:173], v[42:45]
	v_mfma_f32_16x16x32_bf16 v[30:33], v[66:69], v[178:181], v[30:33]
	v_mfma_f32_16x16x32_bf16 v[26:29], v[74:77], v[178:181], v[26:29]
	v_mfma_f32_16x16x32_bf16 v[14:17], v[66:69], v[186:189], v[14:17]
	v_mfma_f32_16x16x32_bf16 v[10:13], v[74:77], v[186:189], v[10:13]
	v_mfma_f32_16x16x32_bf16 v[62:65], v[70:73], v[166:169], v[62:65]
	v_mfma_f32_16x16x32_bf16 v[58:61], v[78:81], v[166:169], v[58:61]
	v_mfma_f32_16x16x32_bf16 v[46:49], v[70:73], v[174:177], v[46:49]
	v_mfma_f32_16x16x32_bf16 v[42:45], v[78:81], v[174:177], v[42:45]
	v_mfma_f32_16x16x32_bf16 v[30:33], v[70:73], v[182:185], v[30:33]
	v_mfma_f32_16x16x32_bf16 v[26:29], v[78:81], v[182:185], v[26:29]
	v_mfma_f32_16x16x32_bf16 v[14:17], v[70:73], v[190:193], v[14:17]
	v_mfma_f32_16x16x32_bf16 v[10:13], v[78:81], v[190:193], v[10:13]
	v_mfma_f32_16x16x32_bf16 v[54:57], v[82:85], v[162:165], v[54:57]
	v_mfma_f32_16x16x32_bf16 v[50:53], v[90:93], v[162:165], v[50:53]
	v_mfma_f32_16x16x32_bf16 v[38:41], v[82:85], v[170:173], v[38:41]
	v_mfma_f32_16x16x32_bf16 v[34:37], v[90:93], v[170:173], v[34:37]
	v_mfma_f32_16x16x32_bf16 v[22:25], v[82:85], v[178:181], v[22:25]
	v_mfma_f32_16x16x32_bf16 v[18:21], v[90:93], v[178:181], v[18:21]
	v_mfma_f32_16x16x32_bf16 v[6:9], v[82:85], v[186:189], v[6:9]
	v_mfma_f32_16x16x32_bf16 v[2:5], v[90:93], v[186:189], v[2:5]
	v_mfma_f32_16x16x32_bf16 v[54:57], v[86:89], v[166:169], v[54:57]
	v_mfma_f32_16x16x32_bf16 v[50:53], v[94:97], v[166:169], v[50:53]
	v_mfma_f32_16x16x32_bf16 v[38:41], v[86:89], v[174:177], v[38:41]
	v_mfma_f32_16x16x32_bf16 v[34:37], v[94:97], v[174:177], v[34:37]
	v_mfma_f32_16x16x32_bf16 v[22:25], v[86:89], v[182:185], v[22:25]
	v_mfma_f32_16x16x32_bf16 v[18:21], v[94:97], v[182:185], v[18:21]
	v_mfma_f32_16x16x32_bf16 v[6:9], v[86:89], v[190:193], v[6:9]
	v_mfma_f32_16x16x32_bf16 v[2:5], v[94:97], v[190:193], v[2:5]
	s_setprio 0
	s_barrier
	s_add_i32 s63, 0, 0x18000
	s_add_i32 s66, 0, 0x1c000
	v_add_u32_e32 v78, s63, v251
	v_add_u32_e32 v94, s66, v251
	ds_read_b128 v[66:69], v78
	ds_read_b128 v[70:73], v78 offset:1024
	ds_read_b128 v[74:77], v78 offset:2048
	ds_read_b128 v[78:81], v78 offset:3072
	ds_read_b128 v[82:85], v94
	ds_read_b128 v[86:89], v94 offset:1024
	ds_read_b128 v[90:93], v94 offset:2048
	ds_read_b128 v[94:97], v94 offset:3072
	s_add_u32 s34, s46, 0x80000
	s_addc_u32 s35, s47, 0
	s_mov_b32 m0, s53
	v_lshl_add_u64 v[202:203], s[34:35], 0, v[210:211]
	ds_read_b128 v[162:165], v244 offset:32768
	ds_read_b128 v[166:169], v244 offset:33792
	ds_read_b128 v[170:173], v244 offset:34816
	ds_read_b128 v[174:177], v244 offset:35840
	ds_read_b128 v[178:181], v244 offset:36864
	ds_read_b128 v[182:185], v244 offset:37888
	ds_read_b128 v[186:189], v244 offset:38912
	ds_read_b128 v[190:193], v244 offset:39936
	global_load_lds_dwordx4 v[202:203], off
	v_lshl_add_u64 v[202:203], s[34:35], 0, v[216:217]
	s_mov_b32 m0, s54
	s_nop 0
	global_load_lds_dwordx4 v[202:203], off
	s_waitcnt vmcnt(8) lgkmcnt(0)
	s_barrier
	s_setprio 1
	v_mfma_f32_16x16x32_bf16 v[158:161], v[66:69], v[162:165], v[158:161]
	v_mfma_f32_16x16x32_bf16 v[154:157], v[74:77], v[162:165], v[154:157]
	v_mfma_f32_16x16x32_bf16 v[142:145], v[66:69], v[170:173], v[142:145]
	v_mfma_f32_16x16x32_bf16 v[138:141], v[74:77], v[170:173], v[138:141]
	v_mfma_f32_16x16x32_bf16 v[126:129], v[66:69], v[178:181], v[126:129]
	v_mfma_f32_16x16x32_bf16 v[122:125], v[74:77], v[178:181], v[122:125]
	v_mfma_f32_16x16x32_bf16 v[110:113], v[66:69], v[186:189], v[110:113]
	v_mfma_f32_16x16x32_bf16 v[106:109], v[74:77], v[186:189], v[106:109]
	v_mfma_f32_16x16x32_bf16 v[158:161], v[70:73], v[166:169], v[158:161]
	v_mfma_f32_16x16x32_bf16 v[154:157], v[78:81], v[166:169], v[154:157]
	v_mfma_f32_16x16x32_bf16 v[142:145], v[70:73], v[174:177], v[142:145]
	v_mfma_f32_16x16x32_bf16 v[138:141], v[78:81], v[174:177], v[138:141]
	v_mfma_f32_16x16x32_bf16 v[126:129], v[70:73], v[182:185], v[126:129]
	v_mfma_f32_16x16x32_bf16 v[122:125], v[78:81], v[182:185], v[122:125]
	v_mfma_f32_16x16x32_bf16 v[110:113], v[70:73], v[190:193], v[110:113]
	v_mfma_f32_16x16x32_bf16 v[106:109], v[78:81], v[190:193], v[106:109]
	v_mfma_f32_16x16x32_bf16 v[150:153], v[82:85], v[162:165], v[150:153]
	v_mfma_f32_16x16x32_bf16 v[146:149], v[90:93], v[162:165], v[146:149]
	v_mfma_f32_16x16x32_bf16 v[134:137], v[82:85], v[170:173], v[134:137]
	v_mfma_f32_16x16x32_bf16 v[130:133], v[90:93], v[170:173], v[130:133]
	v_mfma_f32_16x16x32_bf16 v[118:121], v[82:85], v[178:181], v[118:121]
	v_mfma_f32_16x16x32_bf16 v[114:117], v[90:93], v[178:181], v[114:117]
	v_mfma_f32_16x16x32_bf16 v[102:105], v[82:85], v[186:189], v[102:105]
	v_mfma_f32_16x16x32_bf16 v[98:101], v[90:93], v[186:189], v[98:101]
	v_mfma_f32_16x16x32_bf16 v[150:153], v[86:89], v[166:169], v[150:153]
	v_mfma_f32_16x16x32_bf16 v[146:149], v[94:97], v[166:169], v[146:149]
	v_mfma_f32_16x16x32_bf16 v[134:137], v[86:89], v[174:177], v[134:137]
	v_mfma_f32_16x16x32_bf16 v[130:133], v[94:97], v[174:177], v[130:133]
	v_mfma_f32_16x16x32_bf16 v[118:121], v[86:89], v[182:185], v[118:121]
	v_mfma_f32_16x16x32_bf16 v[114:117], v[94:97], v[182:185], v[114:117]
	v_mfma_f32_16x16x32_bf16 v[102:105], v[86:89], v[190:193], v[102:105]
	v_mfma_f32_16x16x32_bf16 v[98:101], v[94:97], v[190:193], v[98:101]
	s_setprio 0
	s_barrier
	s_add_i32 s34, s63, s44
	v_lshl_add_u64 v[194:195], v[194:195], 0, s[64:65]
	s_mov_b32 m0, s34
	ds_read_b128 v[162:165], v244 offset:49152
	ds_read_b128 v[166:169], v244 offset:50176
	ds_read_b128 v[170:173], v244 offset:51200
	ds_read_b128 v[174:177], v244 offset:52224
	ds_read_b128 v[178:181], v244 offset:53248
	ds_read_b128 v[182:185], v244 offset:54272
	ds_read_b128 v[186:189], v244 offset:55296
	ds_read_b128 v[190:193], v244 offset:56320
	global_load_lds_dwordx4 v[194:195], off
	s_add_i32 m0, s34, 0x2000
	s_add_u32 s34, s42, 0x80080
	v_lshl_add_u64 v[194:195], v[196:197], 0, s[64:65]
	s_addc_u32 s35, s43, 0
	s_add_i32 s42, s66, s44
	global_load_lds_dwordx4 v[194:195], off
	v_lshl_add_u64 v[194:195], s[34:35], 0, v[210:211]
	s_mov_b32 m0, s42
	s_nop 0
	global_load_lds_dwordx4 v[194:195], off
	v_lshl_add_u64 v[194:195], s[34:35], 0, v[216:217]
	s_add_i32 m0, s42, 0x2000
	s_nop 0
	global_load_lds_dwordx4 v[194:195], off
	v_lshl_add_u64 v[194:195], v[198:199], 0, s[64:65]
	s_mov_b32 m0, s55
	s_nop 0
	global_load_lds_dwordx4 v[194:195], off
	v_lshl_add_u64 v[194:195], v[200:201], 0, s[64:65]
	s_mov_b32 m0, s56
	s_nop 0
	global_load_lds_dwordx4 v[194:195], off
	s_waitcnt vmcnt(8) lgkmcnt(0)
	s_barrier
	s_setprio 1
	v_mfma_f32_16x16x32_bf16 v[62:65], v[66:69], v[162:165], v[62:65]
	v_mfma_f32_16x16x32_bf16 v[58:61], v[74:77], v[162:165], v[58:61]
	v_mfma_f32_16x16x32_bf16 v[46:49], v[66:69], v[170:173], v[46:49]
	v_mfma_f32_16x16x32_bf16 v[42:45], v[74:77], v[170:173], v[42:45]
	v_mfma_f32_16x16x32_bf16 v[30:33], v[66:69], v[178:181], v[30:33]
	v_mfma_f32_16x16x32_bf16 v[26:29], v[74:77], v[178:181], v[26:29]
	v_mfma_f32_16x16x32_bf16 v[14:17], v[66:69], v[186:189], v[14:17]
	v_mfma_f32_16x16x32_bf16 v[10:13], v[74:77], v[186:189], v[10:13]
	v_mfma_f32_16x16x32_bf16 v[62:65], v[70:73], v[166:169], v[62:65]
	v_mfma_f32_16x16x32_bf16 v[58:61], v[78:81], v[166:169], v[58:61]
	v_mfma_f32_16x16x32_bf16 v[46:49], v[70:73], v[174:177], v[46:49]
	v_mfma_f32_16x16x32_bf16 v[42:45], v[78:81], v[174:177], v[42:45]
	v_mfma_f32_16x16x32_bf16 v[30:33], v[70:73], v[182:185], v[30:33]
	v_mfma_f32_16x16x32_bf16 v[26:29], v[78:81], v[182:185], v[26:29]
	v_mfma_f32_16x16x32_bf16 v[14:17], v[70:73], v[190:193], v[14:17]
	v_mfma_f32_16x16x32_bf16 v[10:13], v[78:81], v[190:193], v[10:13]
	v_mfma_f32_16x16x32_bf16 v[54:57], v[82:85], v[162:165], v[54:57]
	v_mfma_f32_16x16x32_bf16 v[50:53], v[90:93], v[162:165], v[50:53]
	v_mfma_f32_16x16x32_bf16 v[38:41], v[82:85], v[170:173], v[38:41]
	v_mfma_f32_16x16x32_bf16 v[34:37], v[90:93], v[170:173], v[34:37]
	v_mfma_f32_16x16x32_bf16 v[22:25], v[82:85], v[178:181], v[22:25]
	v_mfma_f32_16x16x32_bf16 v[18:21], v[90:93], v[178:181], v[18:21]
	v_mfma_f32_16x16x32_bf16 v[6:9], v[82:85], v[186:189], v[6:9]
	v_mfma_f32_16x16x32_bf16 v[2:5], v[90:93], v[186:189], v[2:5]
	v_mfma_f32_16x16x32_bf16 v[54:57], v[86:89], v[166:169], v[54:57]
	v_mfma_f32_16x16x32_bf16 v[50:53], v[94:97], v[166:169], v[50:53]
	v_mfma_f32_16x16x32_bf16 v[38:41], v[86:89], v[174:177], v[38:41]
	v_mfma_f32_16x16x32_bf16 v[34:37], v[94:97], v[174:177], v[34:37]
	v_mfma_f32_16x16x32_bf16 v[22:25], v[86:89], v[182:185], v[22:25]
	v_mfma_f32_16x16x32_bf16 v[18:21], v[94:97], v[182:185], v[18:21]
	v_mfma_f32_16x16x32_bf16 v[6:9], v[86:89], v[190:193], v[6:9]
	v_mfma_f32_16x16x32_bf16 v[2:5], v[94:97], v[190:193], v[2:5]
	s_setprio 0
	s_barrier
	s_add_i32 s62, s62, 2
	s_add_u32 s60, s60, 0x100
	s_addc_u32 s61, s61, 0
	s_cmp_gt_u32 s62, 29
	s_mov_b64 s[34:35], s[10:11]
	s_cbranch_scc0 .LBB0_956
	s_and_b64 vcc, exec, s[26:27]
	s_cbranch_vccz .LBB0_959
	s_barrier

.LBB0_1091:
	s_add_u32 s30, s26, 0xfff80080
	s_addc_u32 s31, s27, -1
	s_add_i32 s51, 0, 0x10000
	s_cmp_eq_u32 s50, 28
	s_cselect_b32 s35, s2, s31
	s_cselect_b32 s34, s3, s30
	s_cselect_b32 s31, s19, s49
	s_cselect_b32 s30, s21, s48
	s_add_i32 s54, 0, 0x14000
	v_add_u32_e32 v142, s51, v181
	v_add_u32_e32 v158, s54, v181
	ds_read_b128 v[130:133], v142
	ds_read_b128 v[134:137], v142 offset:1024
	ds_read_b128 v[138:141], v142 offset:2048
	ds_read_b128 v[142:145], v142 offset:3072
	ds_read_b128 v[146:149], v158
	ds_read_b128 v[150:153], v158 offset:1024
	ds_read_b128 v[154:157], v158 offset:2048
	ds_read_b128 v[158:161], v158 offset:3072
	v_lshl_add_u64 v[172:173], s[26:27], 0, v[168:169]
	s_add_i32 m0, s41, 0xc000
	ds_read_b128 v[176:179], v195
	ds_read_b128 v[182:185], v195 offset:1024
	ds_read_b128 v[190:193], v195 offset:2048
	ds_read_b128 v[196:199], v195 offset:3072
	ds_read_b128 v[200:203], v195 offset:4096
	ds_read_b128 v[204:207], v195 offset:5120
	ds_read_b128 v[216:219], v195 offset:6144
	ds_read_b128 v[220:223], v195 offset:7168
	global_load_lds_dwordx4 v[172:173], off
	v_lshl_add_u64 v[172:173], s[26:27], 0, v[170:171]
	s_add_i32 m0, s41, 0xe000
	s_nop 0
	global_load_lds_dwordx4 v[172:173], off
	s_waitcnt vmcnt(8) lgkmcnt(0)
	s_barrier
	s_setprio 1
	v_mfma_f32_16x16x32_bf16 v[126:129], v[130:133], v[176:179], v[126:129]
	v_mfma_f32_16x16x32_bf16 v[122:125], v[138:141], v[176:179], v[122:125]
	v_mfma_f32_16x16x32_bf16 v[110:113], v[130:133], v[190:193], v[110:113]
	v_mfma_f32_16x16x32_bf16 v[106:109], v[138:141], v[190:193], v[106:109]
	v_mfma_f32_16x16x32_bf16 v[94:97], v[130:133], v[200:203], v[94:97]
	v_mfma_f32_16x16x32_bf16 v[90:93], v[138:141], v[200:203], v[90:93]
	v_mfma_f32_16x16x32_bf16 v[78:81], v[130:133], v[216:219], v[78:81]
	v_mfma_f32_16x16x32_bf16 v[74:77], v[138:141], v[216:219], v[74:77]
	v_mfma_f32_16x16x32_bf16 v[126:129], v[134:137], v[182:185], v[126:129]
	v_mfma_f32_16x16x32_bf16 v[122:125], v[142:145], v[182:185], v[122:125]
	v_mfma_f32_16x16x32_bf16 v[110:113], v[134:137], v[196:199], v[110:113]
	v_mfma_f32_16x16x32_bf16 v[106:109], v[142:145], v[196:199], v[106:109]
	v_mfma_f32_16x16x32_bf16 v[94:97], v[134:137], v[204:207], v[94:97]
	v_mfma_f32_16x16x32_bf16 v[90:93], v[142:145], v[204:207], v[90:93]
	v_mfma_f32_16x16x32_bf16 v[78:81], v[134:137], v[220:223], v[78:81]
	v_mfma_f32_16x16x32_bf16 v[74:77], v[142:145], v[220:223], v[74:77]
	v_mfma_f32_16x16x32_bf16 v[118:121], v[146:149], v[176:179], v[118:121]
	v_mfma_f32_16x16x32_bf16 v[114:117], v[154:157], v[176:179], v[114:117]
	v_mfma_f32_16x16x32_bf16 v[102:105], v[146:149], v[190:193], v[102:105]
	v_mfma_f32_16x16x32_bf16 v[98:101], v[154:157], v[190:193], v[98:101]
	v_mfma_f32_16x16x32_bf16 v[86:89], v[146:149], v[200:203], v[86:89]
	v_mfma_f32_16x16x32_bf16 v[82:85], v[154:157], v[200:203], v[82:85]
	v_mfma_f32_16x16x32_bf16 v[70:73], v[146:149], v[216:219], v[70:73]
	v_mfma_f32_16x16x32_bf16 v[66:69], v[154:157], v[216:219], v[66:69]
	v_mfma_f32_16x16x32_bf16 v[118:121], v[150:153], v[182:185], v[118:121]
	v_mfma_f32_16x16x32_bf16 v[114:117], v[158:161], v[182:185], v[114:117]
	v_mfma_f32_16x16x32_bf16 v[102:105], v[150:153], v[196:199], v[102:105]
	v_mfma_f32_16x16x32_bf16 v[98:101], v[158:161], v[196:199], v[98:101]
	v_mfma_f32_16x16x32_bf16 v[86:89], v[150:153], v[204:207], v[86:89]
	v_mfma_f32_16x16x32_bf16 v[82:85], v[158:161], v[204:207], v[82:85]
	v_mfma_f32_16x16x32_bf16 v[70:73], v[150:153], v[220:223], v[70:73]
	v_mfma_f32_16x16x32_bf16 v[66:69], v[158:161], v[220:223], v[66:69]
	s_setprio 0
	s_barrier
	s_add_i32 s51, s51, s40
	v_lshl_add_u64 v[172:173], s[30:31], 0, v[210:211]
	s_mov_b32 m0, s51
	ds_read_b128 v[176:179], v195 offset:16384
	ds_read_b128 v[182:185], v195 offset:17408
	ds_read_b128 v[190:193], v195 offset:18432
	ds_read_b128 v[196:199], v195 offset:19456
	ds_read_b128 v[200:203], v195 offset:20480
	ds_read_b128 v[204:207], v195 offset:21504
	ds_read_b128 v[216:219], v195 offset:22528
	ds_read_b128 v[220:223], v195 offset:23552
	global_load_lds_dwordx4 v[172:173], off
	s_add_i32 m0, s51, 0x2000
	s_add_u32 s52, s30, 0x80000
	v_lshl_add_u64 v[186:187], s[30:31], 0, v[162:163]
	s_addc_u32 s53, s31, 0
	s_add_i32 s51, s54, s40
	global_load_lds_dwordx4 v[186:187], off
	v_lshl_add_u64 v[208:209], s[52:53], 0, v[210:211]
	s_mov_b32 m0, s51
	v_lshl_add_u64 v[212:213], s[34:35], 0, v[164:165]
	global_load_lds_dwordx4 v[208:209], off
	v_lshl_add_u64 v[208:209], s[52:53], 0, v[162:163]
	s_add_i32 m0, s51, 0x2000
	s_nop 0
	global_load_lds_dwordx4 v[208:209], off
	v_lshl_add_u64 v[208:209], s[34:35], 0, v[166:167]
	s_mov_b32 m0, s41
	s_nop 0
	global_load_lds_dwordx4 v[208:209], off
	s_mov_b32 m0, s42
	s_nop 0
	global_load_lds_dwordx4 v[212:213], off
	s_waitcnt vmcnt(8) lgkmcnt(0)
	s_barrier
	s_setprio 1
	v_mfma_f32_16x16x32_bf16 v[62:65], v[130:133], v[176:179], v[62:65]
	v_mfma_f32_16x16x32_bf16 v[58:61], v[138:141], v[176:179], v[58:61]
	v_mfma_f32_16x16x32_bf16 v[46:49], v[130:133], v[190:193], v[46:49]
	v_mfma_f32_16x16x32_bf16 v[42:45], v[138:141], v[190:193], v[42:45]
	v_mfma_f32_16x16x32_bf16 v[30:33], v[130:133], v[200:203], v[30:33]
	v_mfma_f32_16x16x32_bf16 v[26:29], v[138:141], v[200:203], v[26:29]
	v_mfma_f32_16x16x32_bf16 v[14:17], v[130:133], v[216:219], v[14:17]
	v_mfma_f32_16x16x32_bf16 v[10:13], v[138:141], v[216:219], v[10:13]
	v_mfma_f32_16x16x32_bf16 v[62:65], v[134:137], v[182:185], v[62:65]
	v_mfma_f32_16x16x32_bf16 v[58:61], v[142:145], v[182:185], v[58:61]
	v_mfma_f32_16x16x32_bf16 v[46:49], v[134:137], v[196:199], v[46:49]
	v_mfma_f32_16x16x32_bf16 v[42:45], v[142:145], v[196:199], v[42:45]
	v_mfma_f32_16x16x32_bf16 v[30:33], v[134:137], v[204:207], v[30:33]
	v_mfma_f32_16x16x32_bf16 v[26:29], v[142:145], v[204:207], v[26:29]
	v_mfma_f32_16x16x32_bf16 v[14:17], v[134:137], v[220:223], v[14:17]
	v_mfma_f32_16x16x32_bf16 v[10:13], v[142:145], v[220:223], v[10:13]
	v_mfma_f32_16x16x32_bf16 v[54:57], v[146:149], v[176:179], v[54:57]
	v_mfma_f32_16x16x32_bf16 v[50:53], v[154:157], v[176:179], v[50:53]
	v_mfma_f32_16x16x32_bf16 v[38:41], v[146:149], v[190:193], v[38:41]
	v_mfma_f32_16x16x32_bf16 v[34:37], v[154:157], v[190:193], v[34:37]
	v_mfma_f32_16x16x32_bf16 v[22:25], v[146:149], v[200:203], v[22:25]
	v_mfma_f32_16x16x32_bf16 v[18:21], v[154:157], v[200:203], v[18:21]
	v_mfma_f32_16x16x32_bf16 v[6:9], v[146:149], v[216:219], v[6:9]
	v_mfma_f32_16x16x32_bf16 v[2:5], v[154:157], v[216:219], v[2:5]
	v_mfma_f32_16x16x32_bf16 v[54:57], v[150:153], v[182:185], v[54:57]
	v_mfma_f32_16x16x32_bf16 v[50:53], v[158:161], v[182:185], v[50:53]
	v_mfma_f32_16x16x32_bf16 v[38:41], v[150:153], v[196:199], v[38:41]
	v_mfma_f32_16x16x32_bf16 v[34:37], v[158:161], v[196:199], v[34:37]
	v_mfma_f32_16x16x32_bf16 v[22:25], v[150:153], v[204:207], v[22:25]
	v_mfma_f32_16x16x32_bf16 v[18:21], v[158:161], v[204:207], v[18:21]
	v_mfma_f32_16x16x32_bf16 v[6:9], v[150:153], v[220:223], v[6:9]
	v_mfma_f32_16x16x32_bf16 v[2:5], v[158:161], v[220:223], v[2:5]
	s_setprio 0
	s_barrier
	s_add_i32 s51, 0, 0x18000
	s_add_i32 s52, 0, 0x1c000
	v_add_u32_e32 v142, s51, v181
	v_add_u32_e32 v158, s52, v181
	ds_read_b128 v[130:133], v142
	ds_read_b128 v[134:137], v142 offset:1024
	ds_read_b128 v[138:141], v142 offset:2048
	ds_read_b128 v[142:145], v142 offset:3072
	ds_read_b128 v[146:149], v158
	ds_read_b128 v[150:153], v158 offset:1024
	ds_read_b128 v[154:157], v158 offset:2048
	ds_read_b128 v[158:161], v158 offset:3072
	s_add_u32 s34, s34, 0x80000
	s_addc_u32 s35, s35, 0
	s_mov_b32 m0, s43
	v_lshl_add_u64 v[214:215], s[34:35], 0, v[166:167]
	ds_read_b128 v[176:179], v195 offset:32768
	ds_read_b128 v[182:185], v195 offset:33792
	ds_read_b128 v[190:193], v195 offset:34816
	ds_read_b128 v[196:199], v195 offset:35840
	ds_read_b128 v[200:203], v195 offset:36864
	ds_read_b128 v[204:207], v195 offset:37888
	ds_read_b128 v[216:219], v195 offset:38912
	ds_read_b128 v[220:223], v195 offset:39936
	global_load_lds_dwordx4 v[214:215], off
	v_lshl_add_u64 v[214:215], s[34:35], 0, v[164:165]
	s_mov_b32 m0, s44
	s_nop 0
	global_load_lds_dwordx4 v[214:215], off
	s_waitcnt vmcnt(8) lgkmcnt(0)
	s_barrier
	s_setprio 1
	v_mfma_f32_16x16x32_bf16 v[126:129], v[130:133], v[176:179], v[126:129]
	v_mfma_f32_16x16x32_bf16 v[122:125], v[138:141], v[176:179], v[122:125]
	v_mfma_f32_16x16x32_bf16 v[110:113], v[130:133], v[190:193], v[110:113]
	v_mfma_f32_16x16x32_bf16 v[106:109], v[138:141], v[190:193], v[106:109]
	v_mfma_f32_16x16x32_bf16 v[94:97], v[130:133], v[200:203], v[94:97]
	v_mfma_f32_16x16x32_bf16 v[90:93], v[138:141], v[200:203], v[90:93]
	v_mfma_f32_16x16x32_bf16 v[78:81], v[130:133], v[216:219], v[78:81]
	v_mfma_f32_16x16x32_bf16 v[74:77], v[138:141], v[216:219], v[74:77]
	v_mfma_f32_16x16x32_bf16 v[126:129], v[134:137], v[182:185], v[126:129]
	v_mfma_f32_16x16x32_bf16 v[122:125], v[142:145], v[182:185], v[122:125]
	v_mfma_f32_16x16x32_bf16 v[110:113], v[134:137], v[196:199], v[110:113]
	v_mfma_f32_16x16x32_bf16 v[106:109], v[142:145], v[196:199], v[106:109]
	v_mfma_f32_16x16x32_bf16 v[94:97], v[134:137], v[204:207], v[94:97]
	v_mfma_f32_16x16x32_bf16 v[90:93], v[142:145], v[204:207], v[90:93]
	v_mfma_f32_16x16x32_bf16 v[78:81], v[134:137], v[220:223], v[78:81]
	v_mfma_f32_16x16x32_bf16 v[74:77], v[142:145], v[220:223], v[74:77]
	v_mfma_f32_16x16x32_bf16 v[118:121], v[146:149], v[176:179], v[118:121]
	v_mfma_f32_16x16x32_bf16 v[114:117], v[154:157], v[176:179], v[114:117]
	v_mfma_f32_16x16x32_bf16 v[102:105], v[146:149], v[190:193], v[102:105]
	v_mfma_f32_16x16x32_bf16 v[98:101], v[154:157], v[190:193], v[98:101]
	v_mfma_f32_16x16x32_bf16 v[86:89], v[146:149], v[200:203], v[86:89]
	v_mfma_f32_16x16x32_bf16 v[82:85], v[154:157], v[200:203], v[82:85]
	v_mfma_f32_16x16x32_bf16 v[70:73], v[146:149], v[216:219], v[70:73]
	v_mfma_f32_16x16x32_bf16 v[66:69], v[154:157], v[216:219], v[66:69]
	v_mfma_f32_16x16x32_bf16 v[118:121], v[150:153], v[182:185], v[118:121]
	v_mfma_f32_16x16x32_bf16 v[114:117], v[158:161], v[182:185], v[114:117]
	v_mfma_f32_16x16x32_bf16 v[102:105], v[150:153], v[196:199], v[102:105]
	v_mfma_f32_16x16x32_bf16 v[98:101], v[158:161], v[196:199], v[98:101]
	v_mfma_f32_16x16x32_bf16 v[86:89], v[150:153], v[204:207], v[86:89]
	v_mfma_f32_16x16x32_bf16 v[82:85], v[158:161], v[204:207], v[82:85]
	v_mfma_f32_16x16x32_bf16 v[70:73], v[150:153], v[220:223], v[70:73]
	v_mfma_f32_16x16x32_bf16 v[66:69], v[158:161], v[220:223], v[66:69]
	s_setprio 0
	s_barrier
	s_add_i32 s34, s51, s40
	v_lshl_add_u64 v[172:173], v[172:173], 0, s[64:65]
	s_mov_b32 m0, s34
	ds_read_b128 v[176:179], v195 offset:49152
	ds_read_b128 v[182:185], v195 offset:50176
	ds_read_b128 v[190:193], v195 offset:51200
	ds_read_b128 v[196:199], v195 offset:52224
	ds_read_b128 v[200:203], v195 offset:53248
	ds_read_b128 v[204:207], v195 offset:54272
	ds_read_b128 v[216:219], v195 offset:55296
	ds_read_b128 v[220:223], v195 offset:56320
	global_load_lds_dwordx4 v[172:173], off
	s_add_i32 m0, s34, 0x2000
	s_add_u32 s30, s30, 0x80080
	v_lshl_add_u64 v[172:173], v[186:187], 0, s[64:65]
	s_addc_u32 s31, s31, 0
	s_add_i32 s34, s52, s40
	global_load_lds_dwordx4 v[172:173], off
	v_lshl_add_u64 v[172:173], s[30:31], 0, v[210:211]
	s_mov_b32 m0, s34
	s_nop 0
	global_load_lds_dwordx4 v[172:173], off
	v_lshl_add_u64 v[172:173], s[30:31], 0, v[162:163]
	s_add_i32 m0, s34, 0x2000
	s_nop 0
	global_load_lds_dwordx4 v[172:173], off
	v_lshl_add_u64 v[172:173], v[208:209], 0, s[64:65]
	s_mov_b32 m0, s45
	s_nop 0
	global_load_lds_dwordx4 v[172:173], off
	v_lshl_add_u64 v[172:173], v[212:213], 0, s[64:65]
	s_mov_b32 m0, s46
	s_nop 0
	global_load_lds_dwordx4 v[172:173], off
	s_waitcnt vmcnt(8) lgkmcnt(0)
	s_barrier
	s_setprio 1
	v_mfma_f32_16x16x32_bf16 v[62:65], v[130:133], v[176:179], v[62:65]
	v_mfma_f32_16x16x32_bf16 v[58:61], v[138:141], v[176:179], v[58:61]
	v_mfma_f32_16x16x32_bf16 v[46:49], v[130:133], v[190:193], v[46:49]
	v_mfma_f32_16x16x32_bf16 v[42:45], v[138:141], v[190:193], v[42:45]
	v_mfma_f32_16x16x32_bf16 v[30:33], v[130:133], v[200:203], v[30:33]
	v_mfma_f32_16x16x32_bf16 v[26:29], v[138:141], v[200:203], v[26:29]
	v_mfma_f32_16x16x32_bf16 v[14:17], v[130:133], v[216:219], v[14:17]
	v_mfma_f32_16x16x32_bf16 v[10:13], v[138:141], v[216:219], v[10:13]
	v_mfma_f32_16x16x32_bf16 v[62:65], v[134:137], v[182:185], v[62:65]
	v_mfma_f32_16x16x32_bf16 v[58:61], v[142:145], v[182:185], v[58:61]
	v_mfma_f32_16x16x32_bf16 v[46:49], v[134:137], v[196:199], v[46:49]
	v_mfma_f32_16x16x32_bf16 v[42:45], v[142:145], v[196:199], v[42:45]
	v_mfma_f32_16x16x32_bf16 v[30:33], v[134:137], v[204:207], v[30:33]
	v_mfma_f32_16x16x32_bf16 v[26:29], v[142:145], v[204:207], v[26:29]
	v_mfma_f32_16x16x32_bf16 v[14:17], v[134:137], v[220:223], v[14:17]
	v_mfma_f32_16x16x32_bf16 v[10:13], v[142:145], v[220:223], v[10:13]
	v_mfma_f32_16x16x32_bf16 v[54:57], v[146:149], v[176:179], v[54:57]
	v_mfma_f32_16x16x32_bf16 v[50:53], v[154:157], v[176:179], v[50:53]
	v_mfma_f32_16x16x32_bf16 v[38:41], v[146:149], v[190:193], v[38:41]
	v_mfma_f32_16x16x32_bf16 v[34:37], v[154:157], v[190:193], v[34:37]
	v_mfma_f32_16x16x32_bf16 v[22:25], v[146:149], v[200:203], v[22:25]
	v_mfma_f32_16x16x32_bf16 v[18:21], v[154:157], v[200:203], v[18:21]
	v_mfma_f32_16x16x32_bf16 v[6:9], v[146:149], v[216:219], v[6:9]
	v_mfma_f32_16x16x32_bf16 v[2:5], v[154:157], v[216:219], v[2:5]
	v_mfma_f32_16x16x32_bf16 v[54:57], v[150:153], v[182:185], v[54:57]
	v_mfma_f32_16x16x32_bf16 v[50:53], v[158:161], v[182:185], v[50:53]
	v_mfma_f32_16x16x32_bf16 v[38:41], v[150:153], v[196:199], v[38:41]
	v_mfma_f32_16x16x32_bf16 v[34:37], v[158:161], v[196:199], v[34:37]
	v_mfma_f32_16x16x32_bf16 v[22:25], v[150:153], v[204:207], v[22:25]
	v_mfma_f32_16x16x32_bf16 v[18:21], v[158:161], v[204:207], v[18:21]
	v_mfma_f32_16x16x32_bf16 v[6:9], v[150:153], v[220:223], v[6:9]
	v_mfma_f32_16x16x32_bf16 v[2:5], v[158:161], v[220:223], v[2:5]
	s_setprio 0
	s_barrier
	s_add_i32 s50, s50, 2
	s_add_u32 s26, s26, 0x100
	s_addc_u32 s27, s27, 0
	s_add_u32 s48, s48, 0x100
	s_addc_u32 s49, s49, 0
	s_cmp_gt_u32 s50, 29
	s_cbranch_scc0 .LBB0_1091
	v_readlane_b32 s50, v254, 38
	s_and_b64 vcc, exec, s[16:17]
	v_readlane_b32 s51, v254, 39
	s_cbranch_vccz .LBB0_1094
	s_barrier

.LBB0_1180:
	s_add_u32 s36, s34, 0x100
	s_addc_u32 s37, s35, 0
	s_add_i32 s57, 0, 0x10000
	s_cmpk_eq_i32 s56, 0x7c
	s_cselect_b32 s41, s2, s37
	s_cselect_b32 s40, s3, s36
	s_cselect_b32 s39, s23, s55
	s_cselect_b32 s38, s25, s54
	s_add_i32 s58, 0, 0x14000
	v_add_u32_e32 v78, s57, v233
	v_add_u32_e32 v98, s58, v233
	ds_read_b128 v[66:69], v78
	ds_read_b128 v[70:73], v78 offset:1024
	ds_read_b128 v[74:77], v78 offset:2048
	ds_read_b128 v[78:81], v78 offset:3072
	ds_read_b128 v[82:85], v98
	ds_read_b128 v[86:89], v98 offset:1024
	ds_read_b128 v[94:97], v98 offset:2048
	ds_read_b128 v[98:101], v98 offset:3072
	v_lshl_add_u64 v[200:201], s[34:35], 0, v[196:197]
	s_add_i32 m0, s47, 0xc000
	ds_read_b128 v[162:165], v235
	ds_read_b128 v[166:169], v235 offset:1024
	ds_read_b128 v[170:173], v235 offset:2048
	ds_read_b128 v[174:177], v235 offset:3072
	ds_read_b128 v[178:181], v235 offset:4096
	ds_read_b128 v[182:185], v235 offset:5120
	ds_read_b128 v[186:189], v235 offset:6144
	ds_read_b128 v[190:193], v235 offset:7168
	global_load_lds_dwordx4 v[200:201], off
	v_lshl_add_u64 v[200:201], s[34:35], 0, v[198:199]
	s_add_i32 m0, s47, 0xe000
	s_nop 0
	global_load_lds_dwordx4 v[200:201], off
	s_waitcnt vmcnt(8) lgkmcnt(0)
	s_barrier
	s_setprio 1
	v_mfma_f32_16x16x32_bf16 v[158:161], v[66:69], v[162:165], v[158:161]
	v_mfma_f32_16x16x32_bf16 v[154:157], v[74:77], v[162:165], v[154:157]
	v_mfma_f32_16x16x32_bf16 v[142:145], v[66:69], v[170:173], v[142:145]
	v_mfma_f32_16x16x32_bf16 v[138:141], v[74:77], v[170:173], v[138:141]
	v_mfma_f32_16x16x32_bf16 v[126:129], v[66:69], v[178:181], v[126:129]
	v_mfma_f32_16x16x32_bf16 v[122:125], v[74:77], v[178:181], v[122:125]
	v_mfma_f32_16x16x32_bf16 v[110:113], v[66:69], v[186:189], v[110:113]
	v_mfma_f32_16x16x32_bf16 v[106:109], v[74:77], v[186:189], v[106:109]
	v_mfma_f32_16x16x32_bf16 v[158:161], v[70:73], v[166:169], v[158:161]
	v_mfma_f32_16x16x32_bf16 v[154:157], v[78:81], v[166:169], v[154:157]
	v_mfma_f32_16x16x32_bf16 v[142:145], v[70:73], v[174:177], v[142:145]
	v_mfma_f32_16x16x32_bf16 v[138:141], v[78:81], v[174:177], v[138:141]
	v_mfma_f32_16x16x32_bf16 v[126:129], v[70:73], v[182:185], v[126:129]
	v_mfma_f32_16x16x32_bf16 v[122:125], v[78:81], v[182:185], v[122:125]
	v_mfma_f32_16x16x32_bf16 v[110:113], v[70:73], v[190:193], v[110:113]
	v_mfma_f32_16x16x32_bf16 v[106:109], v[78:81], v[190:193], v[106:109]
	v_mfma_f32_16x16x32_bf16 v[150:153], v[82:85], v[162:165], v[150:153]
	v_mfma_f32_16x16x32_bf16 v[146:149], v[94:97], v[162:165], v[146:149]
	v_mfma_f32_16x16x32_bf16 v[134:137], v[82:85], v[170:173], v[134:137]
	v_mfma_f32_16x16x32_bf16 v[130:133], v[94:97], v[170:173], v[130:133]
	v_mfma_f32_16x16x32_bf16 v[118:121], v[82:85], v[178:181], v[118:121]
	v_mfma_f32_16x16x32_bf16 v[114:117], v[94:97], v[178:181], v[114:117]
	v_mfma_f32_16x16x32_bf16 v[102:105], v[82:85], v[186:189], v[102:105]
	v_mfma_f32_16x16x32_bf16 v[90:93], v[94:97], v[186:189], v[90:93]
	v_mfma_f32_16x16x32_bf16 v[150:153], v[86:89], v[166:169], v[150:153]
	v_mfma_f32_16x16x32_bf16 v[146:149], v[98:101], v[166:169], v[146:149]
	v_mfma_f32_16x16x32_bf16 v[134:137], v[86:89], v[174:177], v[134:137]
	v_mfma_f32_16x16x32_bf16 v[130:133], v[98:101], v[174:177], v[130:133]
	v_mfma_f32_16x16x32_bf16 v[118:121], v[86:89], v[182:185], v[118:121]
	v_mfma_f32_16x16x32_bf16 v[114:117], v[98:101], v[182:185], v[114:117]
	v_mfma_f32_16x16x32_bf16 v[102:105], v[86:89], v[190:193], v[102:105]
	v_mfma_f32_16x16x32_bf16 v[90:93], v[98:101], v[190:193], v[90:93]
	s_setprio 0
	s_barrier
	s_add_i32 s34, s57, s46
	v_lshl_add_u64 v[200:201], s[38:39], 0, v[210:211]
	s_mov_b32 m0, s34
	ds_read_b128 v[162:165], v235 offset:16384
	ds_read_b128 v[166:169], v235 offset:17408
	ds_read_b128 v[170:173], v235 offset:18432
	ds_read_b128 v[174:177], v235 offset:19456
	ds_read_b128 v[178:181], v235 offset:20480
	ds_read_b128 v[182:185], v235 offset:21504
	ds_read_b128 v[186:189], v235 offset:22528
	ds_read_b128 v[190:193], v235 offset:23552
	global_load_lds_dwordx4 v[200:201], off
	s_add_i32 m0, s34, 0x2000
	s_add_u32 s34, s38, 0x200000
	v_lshl_add_u64 v[202:203], s[38:39], 0, v[194:195]
	s_addc_u32 s35, s39, 0
	s_add_i32 s57, s58, s46
	global_load_lds_dwordx4 v[202:203], off
	v_lshl_add_u64 v[204:205], s[34:35], 0, v[210:211]
	s_mov_b32 m0, s57
	v_lshl_add_u64 v[206:207], s[40:41], 0, v[194:195]
	global_load_lds_dwordx4 v[204:205], off
	v_lshl_add_u64 v[204:205], s[34:35], 0, v[194:195]
	s_add_i32 m0, s57, 0x2000
	s_nop 0
	global_load_lds_dwordx4 v[204:205], off
	v_lshl_add_u64 v[204:205], s[40:41], 0, v[210:211]
	s_mov_b32 m0, s47
	s_nop 0
	global_load_lds_dwordx4 v[204:205], off
	s_mov_b32 m0, s48
	s_nop 0
	global_load_lds_dwordx4 v[206:207], off
	s_waitcnt vmcnt(8) lgkmcnt(0)
	s_barrier
	s_setprio 1
	v_mfma_f32_16x16x32_bf16 v[62:65], v[66:69], v[162:165], v[62:65]
	v_mfma_f32_16x16x32_bf16 v[58:61], v[74:77], v[162:165], v[58:61]
	v_mfma_f32_16x16x32_bf16 v[46:49], v[66:69], v[170:173], v[46:49]
	v_mfma_f32_16x16x32_bf16 v[42:45], v[74:77], v[170:173], v[42:45]
	v_mfma_f32_16x16x32_bf16 v[30:33], v[66:69], v[178:181], v[30:33]
	v_mfma_f32_16x16x32_bf16 v[26:29], v[74:77], v[178:181], v[26:29]
	v_mfma_f32_16x16x32_bf16 v[14:17], v[66:69], v[186:189], v[14:17]
	v_mfma_f32_16x16x32_bf16 v[10:13], v[74:77], v[186:189], v[10:13]
	v_mfma_f32_16x16x32_bf16 v[62:65], v[70:73], v[166:169], v[62:65]
	v_mfma_f32_16x16x32_bf16 v[58:61], v[78:81], v[166:169], v[58:61]
	v_mfma_f32_16x16x32_bf16 v[46:49], v[70:73], v[174:177], v[46:49]
	v_mfma_f32_16x16x32_bf16 v[42:45], v[78:81], v[174:177], v[42:45]
	v_mfma_f32_16x16x32_bf16 v[30:33], v[70:73], v[182:185], v[30:33]
	v_mfma_f32_16x16x32_bf16 v[26:29], v[78:81], v[182:185], v[26:29]
	v_mfma_f32_16x16x32_bf16 v[14:17], v[70:73], v[190:193], v[14:17]
	v_mfma_f32_16x16x32_bf16 v[10:13], v[78:81], v[190:193], v[10:13]
	v_mfma_f32_16x16x32_bf16 v[54:57], v[82:85], v[162:165], v[54:57]
	v_mfma_f32_16x16x32_bf16 v[50:53], v[94:97], v[162:165], v[50:53]
	v_mfma_f32_16x16x32_bf16 v[38:41], v[82:85], v[170:173], v[38:41]
	v_mfma_f32_16x16x32_bf16 v[34:37], v[94:97], v[170:173], v[34:37]
	v_mfma_f32_16x16x32_bf16 v[22:25], v[82:85], v[178:181], v[22:25]
	v_mfma_f32_16x16x32_bf16 v[18:21], v[94:97], v[178:181], v[18:21]
	v_mfma_f32_16x16x32_bf16 v[6:9], v[82:85], v[186:189], v[6:9]
	v_mfma_f32_16x16x32_bf16 v[2:5], v[94:97], v[186:189], v[2:5]
	v_mfma_f32_16x16x32_bf16 v[54:57], v[86:89], v[166:169], v[54:57]
	v_mfma_f32_16x16x32_bf16 v[50:53], v[98:101], v[166:169], v[50:53]
	v_mfma_f32_16x16x32_bf16 v[38:41], v[86:89], v[174:177], v[38:41]
	v_mfma_f32_16x16x32_bf16 v[34:37], v[98:101], v[174:177], v[34:37]
	v_mfma_f32_16x16x32_bf16 v[22:25], v[86:89], v[182:185], v[22:25]
	v_mfma_f32_16x16x32_bf16 v[18:21], v[98:101], v[182:185], v[18:21]
	v_mfma_f32_16x16x32_bf16 v[6:9], v[86:89], v[190:193], v[6:9]
	v_mfma_f32_16x16x32_bf16 v[2:5], v[98:101], v[190:193], v[2:5]
	s_setprio 0
	s_barrier
	s_add_i32 s57, 0, 0x18000
	s_add_i32 s58, 0, 0x1c000
	v_add_u32_e32 v78, s57, v233
	v_add_u32_e32 v98, s58, v233
	ds_read_b128 v[66:69], v78
	ds_read_b128 v[70:73], v78 offset:1024
	ds_read_b128 v[74:77], v78 offset:2048
	ds_read_b128 v[78:81], v78 offset:3072
	ds_read_b128 v[82:85], v98
	ds_read_b128 v[86:89], v98 offset:1024
	ds_read_b128 v[94:97], v98 offset:2048
	ds_read_b128 v[98:101], v98 offset:3072
	s_add_u32 s34, s40, 0x200000
	s_addc_u32 s35, s41, 0
	s_mov_b32 m0, s49
	v_lshl_add_u64 v[208:209], s[34:35], 0, v[210:211]
	ds_read_b128 v[162:165], v235 offset:32768
	ds_read_b128 v[166:169], v235 offset:33792
	ds_read_b128 v[170:173], v235 offset:34816
	ds_read_b128 v[174:177], v235 offset:35840
	ds_read_b128 v[178:181], v235 offset:36864
	ds_read_b128 v[182:185], v235 offset:37888
	ds_read_b128 v[186:189], v235 offset:38912
	ds_read_b128 v[190:193], v235 offset:39936
	global_load_lds_dwordx4 v[208:209], off
	v_lshl_add_u64 v[208:209], s[34:35], 0, v[194:195]
	s_mov_b32 m0, s50
	s_nop 0
	global_load_lds_dwordx4 v[208:209], off
	s_waitcnt vmcnt(8) lgkmcnt(0)
	s_barrier
	s_setprio 1
	v_mfma_f32_16x16x32_bf16 v[158:161], v[66:69], v[162:165], v[158:161]
	v_mfma_f32_16x16x32_bf16 v[154:157], v[74:77], v[162:165], v[154:157]
	v_mfma_f32_16x16x32_bf16 v[142:145], v[66:69], v[170:173], v[142:145]
	v_mfma_f32_16x16x32_bf16 v[138:141], v[74:77], v[170:173], v[138:141]
	v_mfma_f32_16x16x32_bf16 v[126:129], v[66:69], v[178:181], v[126:129]
	v_mfma_f32_16x16x32_bf16 v[122:125], v[74:77], v[178:181], v[122:125]
	v_mfma_f32_16x16x32_bf16 v[110:113], v[66:69], v[186:189], v[110:113]
	v_mfma_f32_16x16x32_bf16 v[106:109], v[74:77], v[186:189], v[106:109]
	v_mfma_f32_16x16x32_bf16 v[158:161], v[70:73], v[166:169], v[158:161]
	v_mfma_f32_16x16x32_bf16 v[154:157], v[78:81], v[166:169], v[154:157]
	v_mfma_f32_16x16x32_bf16 v[142:145], v[70:73], v[174:177], v[142:145]
	v_mfma_f32_16x16x32_bf16 v[138:141], v[78:81], v[174:177], v[138:141]
	v_mfma_f32_16x16x32_bf16 v[126:129], v[70:73], v[182:185], v[126:129]
	v_mfma_f32_16x16x32_bf16 v[122:125], v[78:81], v[182:185], v[122:125]
	v_mfma_f32_16x16x32_bf16 v[110:113], v[70:73], v[190:193], v[110:113]
	v_mfma_f32_16x16x32_bf16 v[106:109], v[78:81], v[190:193], v[106:109]
	v_mfma_f32_16x16x32_bf16 v[150:153], v[82:85], v[162:165], v[150:153]
	v_mfma_f32_16x16x32_bf16 v[146:149], v[94:97], v[162:165], v[146:149]
	v_mfma_f32_16x16x32_bf16 v[134:137], v[82:85], v[170:173], v[134:137]
	v_mfma_f32_16x16x32_bf16 v[130:133], v[94:97], v[170:173], v[130:133]
	v_mfma_f32_16x16x32_bf16 v[118:121], v[82:85], v[178:181], v[118:121]
	v_mfma_f32_16x16x32_bf16 v[114:117], v[94:97], v[178:181], v[114:117]
	v_mfma_f32_16x16x32_bf16 v[102:105], v[82:85], v[186:189], v[102:105]
	v_mfma_f32_16x16x32_bf16 v[90:93], v[94:97], v[186:189], v[90:93]
	v_mfma_f32_16x16x32_bf16 v[150:153], v[86:89], v[166:169], v[150:153]
	v_mfma_f32_16x16x32_bf16 v[146:149], v[98:101], v[166:169], v[146:149]
	v_mfma_f32_16x16x32_bf16 v[134:137], v[86:89], v[174:177], v[134:137]
	v_mfma_f32_16x16x32_bf16 v[130:133], v[98:101], v[174:177], v[130:133]
	v_mfma_f32_16x16x32_bf16 v[118:121], v[86:89], v[182:185], v[118:121]
	v_mfma_f32_16x16x32_bf16 v[114:117], v[98:101], v[182:185], v[114:117]
	v_mfma_f32_16x16x32_bf16 v[102:105], v[86:89], v[190:193], v[102:105]
	v_mfma_f32_16x16x32_bf16 v[90:93], v[98:101], v[190:193], v[90:93]
	s_setprio 0
	s_barrier
	s_add_i32 s34, s57, s46
	v_lshl_add_u64 v[200:201], v[200:201], 0, s[64:65]
	s_mov_b32 m0, s34
	ds_read_b128 v[162:165], v235 offset:49152
	ds_read_b128 v[166:169], v235 offset:50176
	ds_read_b128 v[170:173], v235 offset:51200
	ds_read_b128 v[174:177], v235 offset:52224
	ds_read_b128 v[178:181], v235 offset:53248
	ds_read_b128 v[182:185], v235 offset:54272
	ds_read_b128 v[186:189], v235 offset:55296
	ds_read_b128 v[190:193], v235 offset:56320
	global_load_lds_dwordx4 v[200:201], off
	s_add_i32 m0, s34, 0x2000
	s_add_u32 s34, s38, 0x200080
	v_lshl_add_u64 v[200:201], v[202:203], 0, s[64:65]
	s_addc_u32 s35, s39, 0
	s_add_i32 s38, s58, s46
	global_load_lds_dwordx4 v[200:201], off
	v_lshl_add_u64 v[200:201], s[34:35], 0, v[210:211]
	s_mov_b32 m0, s38
	s_nop 0
	global_load_lds_dwordx4 v[200:201], off
	v_lshl_add_u64 v[200:201], s[34:35], 0, v[194:195]
	s_add_i32 m0, s38, 0x2000
	s_nop 0
	global_load_lds_dwordx4 v[200:201], off
	v_lshl_add_u64 v[200:201], v[204:205], 0, s[64:65]
	s_mov_b32 m0, s51
	s_nop 0
	global_load_lds_dwordx4 v[200:201], off
	v_lshl_add_u64 v[200:201], v[206:207], 0, s[64:65]
	s_mov_b32 m0, s52
	s_nop 0
	global_load_lds_dwordx4 v[200:201], off
	s_waitcnt vmcnt(8) lgkmcnt(0)
	s_barrier
	s_setprio 1
	v_mfma_f32_16x16x32_bf16 v[62:65], v[66:69], v[162:165], v[62:65]
	v_mfma_f32_16x16x32_bf16 v[58:61], v[74:77], v[162:165], v[58:61]
	v_mfma_f32_16x16x32_bf16 v[46:49], v[66:69], v[170:173], v[46:49]
	v_mfma_f32_16x16x32_bf16 v[42:45], v[74:77], v[170:173], v[42:45]
	v_mfma_f32_16x16x32_bf16 v[30:33], v[66:69], v[178:181], v[30:33]
	v_mfma_f32_16x16x32_bf16 v[26:29], v[74:77], v[178:181], v[26:29]
	v_mfma_f32_16x16x32_bf16 v[14:17], v[66:69], v[186:189], v[14:17]
	v_mfma_f32_16x16x32_bf16 v[10:13], v[74:77], v[186:189], v[10:13]
	v_mfma_f32_16x16x32_bf16 v[62:65], v[70:73], v[166:169], v[62:65]
	v_mfma_f32_16x16x32_bf16 v[58:61], v[78:81], v[166:169], v[58:61]
	v_mfma_f32_16x16x32_bf16 v[46:49], v[70:73], v[174:177], v[46:49]
	v_mfma_f32_16x16x32_bf16 v[42:45], v[78:81], v[174:177], v[42:45]
	v_mfma_f32_16x16x32_bf16 v[30:33], v[70:73], v[182:185], v[30:33]
	v_mfma_f32_16x16x32_bf16 v[26:29], v[78:81], v[182:185], v[26:29]
	v_mfma_f32_16x16x32_bf16 v[14:17], v[70:73], v[190:193], v[14:17]
	v_mfma_f32_16x16x32_bf16 v[10:13], v[78:81], v[190:193], v[10:13]
	v_mfma_f32_16x16x32_bf16 v[54:57], v[82:85], v[162:165], v[54:57]
	v_mfma_f32_16x16x32_bf16 v[50:53], v[94:97], v[162:165], v[50:53]
	v_mfma_f32_16x16x32_bf16 v[38:41], v[82:85], v[170:173], v[38:41]
	v_mfma_f32_16x16x32_bf16 v[34:37], v[94:97], v[170:173], v[34:37]
	v_mfma_f32_16x16x32_bf16 v[22:25], v[82:85], v[178:181], v[22:25]
	v_mfma_f32_16x16x32_bf16 v[18:21], v[94:97], v[178:181], v[18:21]
	v_mfma_f32_16x16x32_bf16 v[6:9], v[82:85], v[186:189], v[6:9]
	v_mfma_f32_16x16x32_bf16 v[2:5], v[94:97], v[186:189], v[2:5]
	v_mfma_f32_16x16x32_bf16 v[54:57], v[86:89], v[166:169], v[54:57]
	v_mfma_f32_16x16x32_bf16 v[50:53], v[98:101], v[166:169], v[50:53]
	v_mfma_f32_16x16x32_bf16 v[38:41], v[86:89], v[174:177], v[38:41]
	v_mfma_f32_16x16x32_bf16 v[34:37], v[98:101], v[174:177], v[34:37]
	v_mfma_f32_16x16x32_bf16 v[22:25], v[86:89], v[182:185], v[22:25]
	v_mfma_f32_16x16x32_bf16 v[18:21], v[98:101], v[182:185], v[18:21]
	v_mfma_f32_16x16x32_bf16 v[6:9], v[86:89], v[190:193], v[6:9]
	v_mfma_f32_16x16x32_bf16 v[2:5], v[98:101], v[190:193], v[2:5]
	s_setprio 0
	s_barrier
	s_add_i32 s56, s56, 2
	s_add_u32 s54, s54, 0x100
	s_addc_u32 s55, s55, 0
	s_cmpk_gt_u32 s56, 0x7d
	s_mov_b64 s[34:35], s[36:37]
	s_cbranch_scc0 .LBB0_1180
	s_and_b64 vcc, exec, s[20:21]
	s_cbranch_vccz .LBB0_1183
	s_barrier
